# static s_setprio 1 for waves 4-7 inside both GEMM K-loops (reset at loop exit)
# baseline (speedup 1.0000x reference)
; template <int EPI>
; DI void gemm_phase(const P& p, int l, const u16* __restrict__ A, const u16* __restrict__ Bt, int mpx, char* lds) {
;     ...
;   const int tn = t + 1;
;   int m1 = 0, n1 = 0;
;   const bool has_next = tile_coords<EPI>(tn, mpx, m1, n1);
;   const u16* Agn = A + (size_t)m1 * 1024;
;   const u16* Bgn = Bt + (size_t)n1 * 1024;
;   f32x4 acc[8][4];
; #pragma unroll
;   for (int i = 0; i < 8; ++i)
; #pragma unroll
;     for (int j = 0; j < 4; ++j) acc[i][j] = zero4();
;   {
;   const int lane = tid & 63, w = tid >> 6, r = lane & 15, g = lane >> 4, wm = w >> 2, wn = w & 3;
;   __syncthreads();
;   GLOAD(Ag, Bg, 64)
;   __builtin_amdgcn_sched_barrier(0);
;   GCOMPUTE_KS(As0, Bs0, 0)
;   __builtin_amdgcn_sched_barrier(0);
;   GSTORE(As1, Bs1)
;   GLOAD(Ag, Bg, 128)
;   __builtin_amdgcn_sched_barrier(0);
;   GCOMPUTE_KS(As0, Bs0, 1)
.LBB0_69:
	v_lshl_add_u64 v[94:95], s[48:49], 0, v[196:197]
	v_add_co_u32_e32 v96, vcc, s33, v94
	v_lshl_add_u64 v[102:103], s[46:47], 0, v[196:197]
	s_nop 0
	v_addc_co_u32_e32 v97, vcc, 0, v95, vcc
	v_add_co_u32_e32 v98, vcc, s35, v94
	s_waitcnt lgkmcnt(0)
	s_nop 0
	v_addc_co_u32_e32 v99, vcc, 0, v95, vcc
	v_add_co_u32_e32 v100, vcc, s39, v94
	s_barrier
	s_nop 0
	v_addc_co_u32_e32 v101, vcc, 0, v95, vcc
	v_add_co_u32_e32 v104, vcc, s33, v102
	s_nop 1
	v_addc_co_u32_e32 v105, vcc, 0, v103, vcc
	v_add_co_u32_e32 v106, vcc, s35, v102
	global_load_dwordx4 v[2:5], v[94:95], off offset:128
	global_load_dwordx4 v[6:9], v[96:97], off offset:128
	v_addc_co_u32_e32 v107, vcc, 0, v103, vcc
	v_add_co_u32_e32 v110, vcc, s39, v102
	global_load_dwordx4 v[10:13], v[98:99], off offset:128
	global_load_dwordx4 v[14:17], v[100:101], off offset:128
	global_load_dwordx4 v[18:21], v[102:103], off offset:128
	global_load_dwordx4 v[22:25], v[104:105], off offset:128
	v_addc_co_u32_e32 v111, vcc, 0, v103, vcc
	global_load_dwordx4 v[26:29], v[106:107], off offset:128
	global_load_dwordx4 v[30:33], v[110:111], off offset:128
	s_add_i32 s56, s56, 1
	s_mul_i32 s2, s56, s57
	s_add_i32 s2, s2, s84
	s_cmp_ge_u32 s2, s25
	s_cselect_b64 s[40:41], -1, 0
	s_lshr_b32 s42, s2, 2
	s_add_i32 s42, s42, s51
	s_lshl_b32 s58, s42, 8
	s_lshl_b32 s42, s2, 8
	s_and_b32 s59, s42, 0x300
	s_lshl_b32 s42, s59, 11
	s_cmp_lt_u32 s2, s25
	s_cselect_b32 s2, s58, 0
	s_cselect_b32 s44, s42, 0
	s_lshl_b64 s[42:43], s[2:3], 11
	s_add_u32 s42, s16, s42
	s_mov_b32 s64, 1
	s_addc_u32 s43, s17, s43
	ds_read_b128 v[34:37], v227
	ds_read_b128 v[38:41], v207 offset:32768
	ds_read_b128 v[42:45], v207 offset:34816
	ds_read_b128 v[46:49], v227 offset:2048
	ds_read_b128 v[58:61], v207 offset:36864
	ds_read_b128 v[62:65], v207 offset:38912
	ds_read_b128 v[82:85], v227 offset:4096
	ds_read_b128 v[86:89], v227 offset:6144
	s_waitcnt lgkmcnt(6)
	v_mfma_f32_16x16x32_bf16 v[50:53], v[34:37], v[38:41], 0
	s_add_u32 s44, s26, s44
	s_addc_u32 s45, s27, 0
	s_waitcnt lgkmcnt(0)
	v_mfma_f32_16x16x32_bf16 v[126:129], v[86:89], v[38:41], 0
	v_mfma_f32_16x16x32_bf16 v[130:133], v[86:89], v[42:45], 0
	v_mfma_f32_16x16x32_bf16 v[134:137], v[86:89], v[58:61], 0
	v_mfma_f32_16x16x32_bf16 v[138:141], v[86:89], v[62:65], 0
	ds_read_b128 v[86:89], v227 offset:8192
	ds_read_b128 v[90:93], v227 offset:10240
	s_waitcnt lgkmcnt(1)
	v_mfma_f32_16x16x32_bf16 v[142:145], v[86:89], v[38:41], 0
	v_mfma_f32_16x16x32_bf16 v[146:149], v[86:89], v[42:45], 0
	v_mfma_f32_16x16x32_bf16 v[150:153], v[86:89], v[58:61], 0
	v_mfma_f32_16x16x32_bf16 v[154:157], v[86:89], v[62:65], 0
	s_waitcnt lgkmcnt(0)
	v_mfma_f32_16x16x32_bf16 v[158:161], v[90:93], v[38:41], 0
	v_mfma_f32_16x16x32_bf16 v[162:165], v[90:93], v[42:45], 0
	v_mfma_f32_16x16x32_bf16 v[166:169], v[90:93], v[58:61], 0
	v_mfma_f32_16x16x32_bf16 v[170:173], v[90:93], v[62:65], 0
	ds_read_b128 v[86:89], v227 offset:12288
	ds_read_b128 v[90:93], v227 offset:14336
	v_mfma_f32_16x16x32_bf16 v[54:57], v[34:37], v[42:45], 0
	v_mfma_f32_16x16x32_bf16 v[66:69], v[34:37], v[58:61], 0
	v_mfma_f32_16x16x32_bf16 v[34:37], v[34:37], v[62:65], 0
	v_mfma_f32_16x16x32_bf16 v[70:73], v[46:49], v[38:41], 0
	v_mfma_f32_16x16x32_bf16 v[74:77], v[46:49], v[42:45], 0
	v_mfma_f32_16x16x32_bf16 v[78:81], v[46:49], v[58:61], 0
	v_mfma_f32_16x16x32_bf16 v[46:49], v[46:49], v[62:65], 0
	v_mfma_f32_16x16x32_bf16 v[114:117], v[82:85], v[38:41], 0
	v_mfma_f32_16x16x32_bf16 v[118:121], v[82:85], v[42:45], 0
	v_mfma_f32_16x16x32_bf16 v[122:125], v[82:85], v[58:61], 0
	v_mfma_f32_16x16x32_bf16 v[82:85], v[82:85], v[62:65], 0
	s_waitcnt lgkmcnt(1)
	v_mfma_f32_16x16x32_bf16 v[174:177], v[86:89], v[38:41], 0
	v_mfma_f32_16x16x32_bf16 v[178:181], v[86:89], v[42:45], 0
	v_mfma_f32_16x16x32_bf16 v[182:185], v[86:89], v[58:61], 0
	v_mfma_f32_16x16x32_bf16 v[186:189], v[86:89], v[62:65], 0
	s_waitcnt lgkmcnt(0)
	v_mfma_f32_16x16x32_bf16 v[190:193], v[90:93], v[38:41], 0
	v_mfma_f32_16x16x32_bf16 v[212:215], v[90:93], v[42:45], 0
	v_mfma_f32_16x16x32_bf16 v[216:219], v[90:93], v[58:61], 0
	v_mfma_f32_16x16x32_bf16 v[220:223], v[90:93], v[62:65], 0
	s_waitcnt vmcnt(7)
	ds_write_b128 v199, v[2:5]
	s_waitcnt vmcnt(6)
	ds_write_b128 v200, v[6:9]
	s_waitcnt vmcnt(5)
	ds_write_b128 v201, v[10:13]
	s_waitcnt vmcnt(4)
	ds_write_b128 v202, v[14:17]
	s_waitcnt vmcnt(3)
	ds_write_b128 v203, v[18:21]
	s_waitcnt vmcnt(2)
	ds_write_b128 v204, v[22:25]
	s_waitcnt vmcnt(1)
	ds_write_b128 v205, v[26:29]
	s_waitcnt vmcnt(0)
; template <int EPI>
; DI void gemm_phase(const P& p, int l, const u16* __restrict__ A, const u16* __restrict__ Bt, int mpx, char* lds) {
;     ...
;   GLOAD(Ag, Bg, 128)
;   __builtin_amdgcn_sched_barrier(0);
;   GCOMPUTE_KS(As0, Bs0, 1)
;   __builtin_amdgcn_sched_barrier(0);
; #pragma unroll 1
;   for (int kk = 1; kk < 15; kk += 2) {
;     __syncthreads();
;     GSTORE(As0, Bs0)
;     GLOAD(Ag, Bg, (kk + 2) * 64)
	ds_write_b128 v206, v[30:33]
	global_load_dwordx4 v[18:21], v[94:95], off offset:256
	global_load_dwordx4 v[86:89], v[96:97], off offset:256
	global_load_dwordx4 v[90:93], v[98:99], off offset:256
	s_nop 0
	global_load_dwordx4 v[94:97], v[100:101], off offset:256
	s_nop 0
	global_load_dwordx4 v[98:101], v[102:103], off offset:256
	s_nop 0
	global_load_dwordx4 v[102:105], v[104:105], off offset:256
	s_nop 0
	global_load_dwordx4 v[106:109], v[106:107], off offset:256
	s_nop 0
	global_load_dwordx4 v[110:113], v[110:111], off offset:256
	ds_read_b128 v[2:5], v229
	ds_read_b128 v[234:237], v228 offset:32768
	ds_read_b128 v[238:241], v228 offset:34816
	ds_read_b128 v[242:245], v228 offset:36864
	ds_read_b128 v[246:249], v228 offset:38912
	s_waitcnt lgkmcnt(3)
	v_mfma_f32_16x16x32_bf16 v[6:9], v[2:5], v[234:237], v[50:53]
	s_waitcnt lgkmcnt(2)
	v_mfma_f32_16x16x32_bf16 v[10:13], v[2:5], v[238:241], v[54:57]
	s_waitcnt lgkmcnt(1)
	v_mfma_f32_16x16x32_bf16 v[14:17], v[2:5], v[242:245], v[66:69]
	s_waitcnt lgkmcnt(0)
	v_mfma_f32_16x16x32_bf16 v[22:25], v[2:5], v[246:249], v[34:37]
	ds_read_b128 v[2:5], v229 offset:2048
	s_waitcnt lgkmcnt(0)
	v_mfma_f32_16x16x32_bf16 v[26:29], v[2:5], v[234:237], v[70:73]
	v_mfma_f32_16x16x32_bf16 v[30:33], v[2:5], v[238:241], v[74:77]
	v_mfma_f32_16x16x32_bf16 v[34:37], v[2:5], v[242:245], v[78:81]
	v_mfma_f32_16x16x32_bf16 v[38:41], v[2:5], v[246:249], v[46:49]
	ds_read_b128 v[2:5], v229 offset:4096
	s_waitcnt lgkmcnt(0)
	v_mfma_f32_16x16x32_bf16 v[42:45], v[2:5], v[234:237], v[114:117]
	v_mfma_f32_16x16x32_bf16 v[46:49], v[2:5], v[238:241], v[118:121]
	v_mfma_f32_16x16x32_bf16 v[50:53], v[2:5], v[242:245], v[122:125]
	v_mfma_f32_16x16x32_bf16 v[54:57], v[2:5], v[246:249], v[82:85]
	ds_read_b128 v[2:5], v229 offset:6144
	s_waitcnt lgkmcnt(0)
	v_mfma_f32_16x16x32_bf16 v[58:61], v[2:5], v[234:237], v[126:129]
	v_mfma_f32_16x16x32_bf16 v[62:65], v[2:5], v[238:241], v[130:133]
	v_mfma_f32_16x16x32_bf16 v[66:69], v[2:5], v[242:245], v[134:137]
	v_mfma_f32_16x16x32_bf16 v[70:73], v[2:5], v[246:249], v[138:141]
	ds_read_b128 v[2:5], v229 offset:8192
	s_waitcnt lgkmcnt(0)
	v_mfma_f32_16x16x32_bf16 v[74:77], v[2:5], v[234:237], v[142:145]
	v_mfma_f32_16x16x32_bf16 v[78:81], v[2:5], v[238:241], v[146:149]
	v_mfma_f32_16x16x32_bf16 v[82:85], v[2:5], v[242:245], v[150:153]
	v_mfma_f32_16x16x32_bf16 v[114:117], v[2:5], v[246:249], v[154:157]
	ds_read_b128 v[2:5], v229 offset:10240
	s_waitcnt lgkmcnt(0)
	v_mfma_f32_16x16x32_bf16 v[118:121], v[2:5], v[234:237], v[158:161]
	v_mfma_f32_16x16x32_bf16 v[122:125], v[2:5], v[238:241], v[162:165]
	v_mfma_f32_16x16x32_bf16 v[126:129], v[2:5], v[242:245], v[166:169]
	v_mfma_f32_16x16x32_bf16 v[130:133], v[2:5], v[246:249], v[170:173]
	ds_read_b128 v[2:5], v229 offset:12288
	s_waitcnt lgkmcnt(0)
	v_mfma_f32_16x16x32_bf16 v[134:137], v[2:5], v[234:237], v[174:177]
	v_mfma_f32_16x16x32_bf16 v[138:141], v[2:5], v[238:241], v[178:181]
	v_mfma_f32_16x16x32_bf16 v[142:145], v[2:5], v[242:245], v[182:185]
	v_mfma_f32_16x16x32_bf16 v[146:149], v[2:5], v[246:249], v[186:189]
	ds_read_b128 v[2:5], v229 offset:14336
	s_waitcnt lgkmcnt(0)
	v_mfma_f32_16x16x32_bf16 v[150:153], v[2:5], v[234:237], v[190:193]
	v_mfma_f32_16x16x32_bf16 v[154:157], v[2:5], v[238:241], v[212:215]
	v_mfma_f32_16x16x32_bf16 v[158:161], v[2:5], v[242:245], v[216:219]
	v_mfma_f32_16x16x32_bf16 v[2:5], v[2:5], v[246:249], v[220:223]
	s_movk_i32 s62, 0x100
	s_mov_b64 s[52:53], s[46:47]
	s_mov_b64 s[54:55], s[48:49]
	v_add_u32_e32 v208, s33, v196
	v_add_u32_e32 v209, s35, v196
	v_add_u32_e32 v210, s39, v196
	v_readfirstlane_b32 s98, v195
	s_cmpk_lt_u32 s98, 0x100
	s_cbranch_scc1 .Lprio_skip_0
	s_setprio 1
.Lprio_skip_0:
	s_barrier
	ds_read_b128 v[212:215], v230
	ds_read_b128 v[216:219], v230 offset:2048
	ds_read_b128 v[220:223], v230 offset:4096
	ds_read_b128 v[234:237], v230 offset:6144
	ds_read_b128 v[238:241], v231
	ds_read_b128 v[242:245], v231 offset:2048
	ds_read_b128 v[246:249], v231 offset:4096
	ds_read_b128 v[250:253], v231 offset:6144
	global_load_dwordx4 v[162:165], v196, s[54:55] offset:384
	global_load_dwordx4 v[166:169], v208, s[54:55] offset:384
	global_load_dwordx4 v[170:173], v209, s[54:55] offset:384
	global_load_dwordx4 v[174:177], v210, s[54:55] offset:384
	global_load_dwordx4 v[178:181], v196, s[52:53] offset:384
	global_load_dwordx4 v[182:185], v208, s[52:53] offset:384
	global_load_dwordx4 v[186:189], v209, s[52:53] offset:384
	global_load_dwordx4 v[190:193], v210, s[52:53] offset:384

; #define GCOMPUTE(AS, BS) GCOMPUTE_KS(AS, BS, 0) GCOMPUTE_KS(AS, BS, 1)
; template <int EPI>
; DI void gemm_phase(const P& p, int l, const u16* __restrict__ A, const u16* __restrict__ Bt, int mpx, char* lds) {
;     ...
;   __syncthreads();
;   __builtin_amdgcn_sched_barrier(0);
;   GCOMPUTE(As1, Bs1)
;   __builtin_amdgcn_sched_barrier(0);
;   }
;   __syncthreads();
.Lgemm_out_exit:
	s_setprio 0
	v_mfma_f32_16x16x32_bf16 v[134:137], v[246:249], v[162:165], v[134:137]
	v_mfma_f32_16x16x32_bf16 v[138:141], v[246:249], v[166:169], v[138:141]
	v_mfma_f32_16x16x32_bf16 v[142:145], v[246:249], v[170:173], v[142:145]
	v_mfma_f32_16x16x32_bf16 v[146:149], v[246:249], v[174:177], v[146:149]
	v_mfma_f32_16x16x32_bf16 v[150:153], v[250:253], v[162:165], v[150:153]
	v_mfma_f32_16x16x32_bf16 v[154:157], v[250:253], v[166:169], v[154:157]
	v_mfma_f32_16x16x32_bf16 v[158:161], v[250:253], v[170:173], v[158:161]
	v_mfma_f32_16x16x32_bf16 v[2:5], v[250:253], v[174:177], v[2:5]
	s_barrier
	ds_read_b128 v[162:165], v231
	ds_read_b128 v[166:169], v230
	ds_read_b128 v[170:173], v230 offset:2048
	ds_read_b128 v[174:177], v230 offset:4096
	ds_read_b128 v[178:181], v230 offset:6144
	s_waitcnt lgkmcnt(3)
	v_mfma_f32_16x16x32_bf16 v[6:9], v[162:165], v[166:169], v[6:9]
	s_waitcnt lgkmcnt(2)
	v_mfma_f32_16x16x32_bf16 v[10:13], v[162:165], v[170:173], v[10:13]
	s_waitcnt lgkmcnt(1)
	v_mfma_f32_16x16x32_bf16 v[14:17], v[162:165], v[174:177], v[14:17]
	s_waitcnt lgkmcnt(0)
	v_mfma_f32_16x16x32_bf16 v[22:25], v[162:165], v[178:181], v[22:25]
	ds_read_b128 v[162:165], v231 offset:2048
	s_waitcnt lgkmcnt(0)
	v_mfma_f32_16x16x32_bf16 v[26:29], v[162:165], v[166:169], v[26:29]
	v_mfma_f32_16x16x32_bf16 v[30:33], v[162:165], v[170:173], v[30:33]
	v_mfma_f32_16x16x32_bf16 v[34:37], v[162:165], v[174:177], v[34:37]
	v_mfma_f32_16x16x32_bf16 v[38:41], v[162:165], v[178:181], v[38:41]
	ds_read_b128 v[162:165], v231 offset:4096
	s_waitcnt lgkmcnt(0)
	v_mfma_f32_16x16x32_bf16 v[42:45], v[162:165], v[166:169], v[42:45]
	v_mfma_f32_16x16x32_bf16 v[46:49], v[162:165], v[170:173], v[46:49]
	v_mfma_f32_16x16x32_bf16 v[50:53], v[162:165], v[174:177], v[50:53]
	v_mfma_f32_16x16x32_bf16 v[54:57], v[162:165], v[178:181], v[54:57]
	ds_read_b128 v[162:165], v231 offset:6144
	s_waitcnt lgkmcnt(0)
	v_mfma_f32_16x16x32_bf16 v[58:61], v[162:165], v[166:169], v[58:61]
	v_mfma_f32_16x16x32_bf16 v[62:65], v[162:165], v[170:173], v[62:65]
	v_mfma_f32_16x16x32_bf16 v[66:69], v[162:165], v[174:177], v[66:69]
	v_mfma_f32_16x16x32_bf16 v[162:165], v[162:165], v[178:181], v[70:73]
	s_nop 2
	ds_read_b128 v[70:73], v231 offset:8192
	s_waitcnt lgkmcnt(0)
	v_mfma_f32_16x16x32_bf16 v[182:185], v[70:73], v[166:169], v[74:77]
	s_nop 2
	ds_read_b128 v[74:77], v233
	v_mfma_f32_16x16x32_bf16 v[186:189], v[70:73], v[170:173], v[78:81]
	v_mfma_f32_16x16x32_bf16 v[190:193], v[70:73], v[174:177], v[82:85]
	v_mfma_f32_16x16x32_bf16 v[212:215], v[70:73], v[178:181], v[114:117]
	ds_read_b128 v[70:73], v231 offset:10240
	s_waitcnt lgkmcnt(0)
	v_mfma_f32_16x16x32_bf16 v[216:219], v[70:73], v[166:169], v[118:121]
	v_mfma_f32_16x16x32_bf16 v[220:223], v[70:73], v[170:173], v[122:125]
	v_mfma_f32_16x16x32_bf16 v[234:237], v[70:73], v[174:177], v[126:129]
	v_mfma_f32_16x16x32_bf16 v[238:241], v[70:73], v[178:181], v[130:133]
	ds_read_b128 v[70:73], v231 offset:12288
	s_waitcnt lgkmcnt(0)
	v_mfma_f32_16x16x32_bf16 v[242:245], v[70:73], v[166:169], v[134:137]
	v_mfma_f32_16x16x32_bf16 v[246:249], v[70:73], v[170:173], v[138:141]
	v_mfma_f32_16x16x32_bf16 v[250:253], v[70:73], v[174:177], v[142:145]
	v_mfma_f32_16x16x32_bf16 v[208:211], v[70:73], v[178:181], v[146:149]
	ds_read_b128 v[70:73], v231 offset:14336
	s_waitcnt lgkmcnt(0)
	v_mfma_f32_16x16x32_bf16 v[178:181], v[70:73], v[178:181], v[2:5]
	s_nop 2
	ds_read_b128 v[2:5], v232
	s_waitcnt lgkmcnt(0)
	v_mfma_f32_16x16x32_bf16 v[146:149], v[74:77], v[2:5], v[6:9]
	s_nop 2
	ds_read_b128 v[6:9], v232 offset:2048
	v_mfma_f32_16x16x32_bf16 v[170:173], v[70:73], v[170:173], v[154:157]
	s_waitcnt lgkmcnt(0)
	v_mfma_f32_16x16x32_bf16 v[154:157], v[74:77], v[6:9], v[10:13]
	s_nop 2
	ds_read_b128 v[10:13], v232 offset:4096
	v_mfma_f32_16x16x32_bf16 v[166:169], v[70:73], v[166:169], v[150:153]
	s_waitcnt lgkmcnt(0)
	v_mfma_f32_16x16x32_bf16 v[150:153], v[74:77], v[10:13], v[14:17]
	s_nop 2
	ds_read_b128 v[14:17], v232 offset:6144
	v_mfma_f32_16x16x32_bf16 v[174:177], v[70:73], v[174:177], v[158:161]
	s_waitcnt lgkmcnt(0)
	v_mfma_f32_16x16x32_bf16 v[158:161], v[74:77], v[14:17], v[22:25]
	s_nop 2
	ds_read_b128 v[22:25], v233 offset:2048
	s_waitcnt lgkmcnt(0)
	v_mfma_f32_16x16x32_bf16 v[138:141], v[22:25], v[2:5], v[26:29]
	s_nop 2
	ds_read_b128 v[26:29], v233 offset:12288
	v_mfma_f32_16x16x32_bf16 v[142:145], v[22:25], v[6:9], v[30:33]
	v_mfma_f32_16x16x32_bf16 v[130:133], v[22:25], v[10:13], v[34:37]
	v_mfma_f32_16x16x32_bf16 v[134:137], v[22:25], v[14:17], v[38:41]
	ds_read_b128 v[22:25], v233 offset:4096
	s_waitcnt lgkmcnt(0)
	v_mfma_f32_16x16x32_bf16 v[122:125], v[22:25], v[2:5], v[42:45]
	v_mfma_f32_16x16x32_bf16 v[126:129], v[22:25], v[6:9], v[46:49]
	v_mfma_f32_16x16x32_bf16 v[114:117], v[22:25], v[10:13], v[50:53]
	v_mfma_f32_16x16x32_bf16 v[118:121], v[22:25], v[14:17], v[54:57]
	ds_read_b128 v[22:25], v233 offset:6144
	s_waitcnt lgkmcnt(0)
	v_mfma_f32_16x16x32_bf16 v[78:81], v[22:25], v[2:5], v[58:61]
	v_mfma_f32_16x16x32_bf16 v[82:85], v[22:25], v[6:9], v[62:65]
	v_mfma_f32_16x16x32_bf16 v[70:73], v[22:25], v[10:13], v[66:69]
	v_mfma_f32_16x16x32_bf16 v[74:77], v[22:25], v[14:17], v[162:165]
	ds_read_b128 v[22:25], v233 offset:8192
	s_nop 1
	ds_read_b128 v[162:165], v233 offset:14336
	s_waitcnt lgkmcnt(1)
	v_mfma_f32_16x16x32_bf16 v[62:65], v[22:25], v[2:5], v[182:185]
	v_mfma_f32_16x16x32_bf16 v[66:69], v[22:25], v[6:9], v[186:189]
	v_mfma_f32_16x16x32_bf16 v[54:57], v[22:25], v[10:13], v[190:193]
	v_mfma_f32_16x16x32_bf16 v[58:61], v[22:25], v[14:17], v[212:215]
	ds_read_b128 v[22:25], v233 offset:10240
	s_waitcnt lgkmcnt(0)
	v_mfma_f32_16x16x32_bf16 v[46:49], v[22:25], v[2:5], v[216:219]
	v_mfma_f32_16x16x32_bf16 v[50:53], v[22:25], v[6:9], v[220:223]
	v_mfma_f32_16x16x32_bf16 v[38:41], v[22:25], v[10:13], v[234:237]
	v_mfma_f32_16x16x32_bf16 v[42:45], v[22:25], v[14:17], v[238:241]
	v_mfma_f32_16x16x32_bf16 v[30:33], v[26:29], v[2:5], v[242:245]
	v_mfma_f32_16x16x32_bf16 v[34:37], v[26:29], v[6:9], v[246:249]
	v_mfma_f32_16x16x32_bf16 v[22:25], v[26:29], v[10:13], v[250:253]
	v_mfma_f32_16x16x32_bf16 v[26:29], v[26:29], v[14:17], v[208:211]
	v_mfma_f32_16x16x32_bf16 v[166:169], v[162:165], v[2:5], v[166:169]
	v_mfma_f32_16x16x32_bf16 v[170:173], v[162:165], v[6:9], v[170:173]
	v_mfma_f32_16x16x32_bf16 v[2:5], v[162:165], v[10:13], v[174:177]
	v_mfma_f32_16x16x32_bf16 v[6:9], v[162:165], v[14:17], v[178:181]
	v_mov_b32_e32 v14, v195
	s_barrier
; DI int tidx() { int t = threadIdx.x; asm volatile("" : "+v"(t)); return t; }
; template <int EPI>
; DI void gemm_phase(const P& p, int l, const u16* __restrict__ A, const u16* __restrict__ Bt, int mpx, char* lds) {
;     ...
;   GSTORE(As0, Bs0)
;   const int tid_e = tidx();
;   const int lane = tid_e & 63, w = tid_e >> 6, r = lane & 15, g = lane >> 4, wm = w >> 2, wn = w & 3;
;   if constexpr (EPI == 1) {
;     const float alpha = 1.4142135623730951f;
;     float* Cw = (float*)(lds + 65536) + w * (16 * 68);
;     const int mr = m0 < MLAT ? (m0 >> 11) : 16;
;     const int colw = n0 + wn * 64;
;     const float* gate = p.mod + (size_t)(l * 17 + mr) * 3072 + 2048 + colw;
;     const float* xr = ((l == 0) ? (m0 < MLAT ? p.x + (size_t)m0 * 1024 : p.ctx + (size_t)(m0 - MLAT) * 1024)
;                                 : p.out + (size_t)m0 * 1024) + (size_t)(wm * 128) * 1024 + colw;
;     float* Z = (float*)p.slab + (size_t)(m0 + wm * 128) * 1024 + colw;
;     const int c4 = (lane & 15) * 4, rr0 = lane >> 4;
;     const float4 gt = *(const float4*)(gate + c4);
;     float4 xn[4];
; #pragma unroll
;     for (int i = 0; i < 4; ++i) xn[i] = *(const float4*)(xr + (size_t)(rr0 + 4 * i) * 1024 + c4);
; #pragma unroll
;     for (int mi = 0; mi < 8; ++mi) {
;       float4 xv[4];
; #pragma unroll
;       for (int i = 0; i < 4; ++i) xv[i] = xn[i];
;       if (mi < 7) {
; #pragma unroll
;         for (int i = 0; i < 4; ++i) xn[i] = *(const float4*)(xr + (size_t)((mi + 1) * 16 + rr0 + 4 * i) * 1024 + c4);
;       }
; #pragma unroll
;       for (int ni = 0; ni < 4; ++ni)
; #pragma unroll
;         for (int j = 0; j < 4; ++j) Cw[(g * 4 + j) * 68 + ni * 16 + r] = acc[mi][ni][j];
;       __builtin_amdgcn_fence(__ATOMIC_RELEASE, "wavefront");
; #pragma unroll
;       for (int i = 0; i < 4; ++i) {
;         const int row = rr0 + 4 * i;
;         const float4 a = *(const float4*)&Cw[row * 68 + c4];
;         float4 z;
;         z.x = alpha * xv[i].x + gt.x * a.x;
;         z.y = alpha * xv[i].y + gt.y * a.y;
;         z.z = alpha * xv[i].z + gt.z * a.z;
;         z.w = alpha * xv[i].w + gt.w * a.w;
;         *(float4*)(Z + (size_t)(mi * 16 + row) * 1024 + c4) = z;
;       }
	s_waitcnt vmcnt(7)
	ds_write_b128 v198, v[18:21]
	s_waitcnt vmcnt(5)
	ds_write_b128 v198, v[86:89] offset:8192
	s_waitcnt vmcnt(4)
	ds_write_b128 v198, v[90:93] offset:16384
	s_waitcnt vmcnt(3)
	ds_write_b128 v198, v[94:97] offset:24576
	ds_write_b128 v198, v[98:101] offset:32768
	s_waitcnt vmcnt(2)
	ds_write_b128 v198, v[102:105] offset:40960
	s_waitcnt vmcnt(1)
	ds_write_b128 v198, v[106:109] offset:49152
	s_waitcnt vmcnt(0)
	ds_write_b128 v198, v[110:113] offset:57344
	s_movk_i32 s2, 0x1100
	v_lshrrev_b32_e32 v0, 6, v14
	v_mul_lo_u32 v19, v0, s2
	s_min_i32 s2, s60, 0x8000
	s_lshr_b32 s2, s2, 11
	s_mul_i32 s46, s50, 17
	v_and_b32_e32 v0, 0xc0, v14
	s_add_i32 s2, s2, s46
	v_readlane_b32 s64, v255, 28
	v_or_b32_e32 v0, s61, v0
	s_mul_hi_i32 s47, s2, 0x3000
	s_mulk_i32 s2, 0x3000
	v_readlane_b32 s66, v255, 30
	v_readlane_b32 s67, v255, 31
	s_add_u32 s46, s66, s2
	v_lshlrev_b64 v[10:11], 2, v[0:1]
	v_mov_b32_e32 v0, 0x8000
	s_addc_u32 s47, s67, s47
	v_sub_co_u32_e32 v0, vcc, s60, v0
	v_lshl_add_u64 v[12:13], s[46:47], 0, v[10:11]
	s_and_b64 s[46:47], vcc, exec
	v_readfirstlane_b32 s2, v0
	s_cselect_b32 s2, s60, s2
	s_cselect_b32 s48, 0, 16
	s_and_b64 s[46:47], s[0:1], exec
	s_cselect_b32 s46, s48, 0x88
	s_cselect_b32 s2, s2, s60
	s_add_u32 s46, s96, s46
	s_addc_u32 s47, s97, 0
	s_load_dwordx2 s[46:47], s[46:47], 0x0
	v_ashrrev_i32_e32 v0, 1, v14
	v_and_b32_e32 v18, 15, v14
	v_bfe_u32 v88, v14, 4, 2
	s_lshl_b64 s[48:49], s[2:3], 12
	v_and_b32_e32 v14, 0xffffff80, v0
	s_waitcnt lgkmcnt(0)
	s_add_u32 s46, s46, s48
	v_ashrrev_i32_e32 v15, 31, v14
	s_addc_u32 s47, s47, s49
	v_lshlrev_b64 v[16:17], 12, v[14:15]
	v_lshl_add_u64 v[16:17], s[46:47], 0, v[16:17]
	v_add_u32_e32 v14, s60, v14
	v_lshl_add_u64 v[16:17], v[16:17], 0, v[10:11]
	v_ashrrev_i32_e32 v15, 31, v14
	v_lshlrev_b32_e32 v0, 4, v18
	v_lshlrev_b64 v[14:15], 12, v[14:15]
	v_lshlrev_b32_e32 v20, 2, v18
	v_lshl_add_u64 v[16:17], v[16:17], 0, v[0:1]
	v_lshlrev_b32_e32 v86, 12, v88
	v_mov_b32_e32 v87, v1
	v_lshl_add_u64 v[14:15], s[18:19], 0, v[14:15]
	v_lshl_add_u64 v[162:163], v[16:17], 0, v[86:87]
	v_add3_u32 v16, s78, v19, v20
	s_movk_i32 s2, 0x440
	v_lshl_add_u64 v[12:13], v[12:13], 0, v[0:1]
	v_lshl_add_u64 v[10:11], v[14:15], 0, v[10:11]
	v_mad_u32_u24 v165, v88, s2, v16
	s_movk_i32 s2, 0x2000
	v_lshl_add_u64 v[14:15], v[10:11], 0, v[0:1]
	v_add_co_u32_e32 v10, vcc, s2, v12
	ds_write2_b32 v165, v146, v154 offset1:16
	ds_write2_b32 v165, v147, v155 offset0:68 offset1:84
	ds_write2_b32 v165, v148, v156 offset0:136 offset1:152
	ds_write2_b32 v165, v149, v157 offset0:204 offset1:220
	ds_write2_b32 v165, v150, v158 offset0:32 offset1:48
	ds_write2_b32 v165, v151, v159 offset0:100 offset1:116
	ds_write2_b32 v165, v152, v160 offset0:168 offset1:184
	ds_write2_b32 v165, v153, v161 offset0:236 offset1:252
	v_addc_co_u32_e32 v11, vcc, 0, v13, vcc
	v_mad_u32_u24 v17, v18, 12, v16
	global_load_dwordx4 v[18:21], v[10:11], off
	s_nop 0
	global_load_dwordx4 v[10:13], v[162:163], off
	v_or_b32_e32 v0, 4, v88
	v_add_co_u32_e32 v16, vcc, s94, v162
	v_mad_u32_u24 v164, v88, s79, v17
	v_mad_u32_u24 v158, v0, s79, v17
	v_addc_co_u32_e32 v17, vcc, 0, v163, vcc
	global_load_dwordx4 v[102:105], v[16:17], off
	v_add_co_u32_e32 v16, vcc, s21, v162
	v_lshlrev_b32_e32 v0, 12, v0
	s_nop 0
	v_addc_co_u32_e32 v17, vcc, 0, v163, vcc
	global_load_dwordx4 v[94:97], v[16:17], off
	v_lshl_add_u64 v[156:157], v[14:15], 0, v[0:1]
	v_or_b32_e32 v0, 0x8000, v86
	v_lshl_add_u64 v[154:155], v[14:15], 0, v[0:1]
	v_or_b32_e32 v0, 0xc000, v86
	s_mov_b32 s2, 0xc000
	v_lshl_add_u64 v[152:153], v[14:15], 0, v[86:87]
	v_lshl_add_u64 v[150:151], v[14:15], 0, v[0:1]
	v_add_co_u32_e32 v14, vcc, s2, v162
	s_mov_b32 s2, 0x14000
	s_nop 0
	v_addc_co_u32_e32 v15, vcc, 0, v163, vcc
	global_load_dwordx4 v[86:89], v[14:15], off
	v_add_co_u32_e32 v14, vcc, s85, v162
	s_mov_b32 s46, 0x30000
	s_nop 0
	v_addc_co_u32_e32 v15, vcc, 0, v163, vcc
	global_load_dwordx4 v[146:149], v[14:15], off
	v_add_co_u32_e32 v14, vcc, s2, v162
	s_mov_b32 s2, 0x18000
	s_nop 0
	v_addc_co_u32_e32 v15, vcc, 0, v163, vcc
	global_load_dwordx4 v[106:109], v[14:15], off
	v_add_co_u32_e32 v14, vcc, s2, v162
	s_mov_b32 s2, 0x1c000
	s_nop 0
	v_addc_co_u32_e32 v15, vcc, 0, v163, vcc
	global_load_dwordx4 v[98:101], v[14:15], off
	v_add_co_u32_e32 v14, vcc, s2, v162
	s_mov_b32 s2, 0x24000
	s_nop 0
	v_addc_co_u32_e32 v15, vcc, 0, v163, vcc
	global_load_dwordx4 v[90:93], v[14:15], off
	ds_read_b128 v[14:17], v164
	s_mov_b32 s60, s58
	s_mov_b32 s61, s59
	s_mov_b64 s[48:49], s[42:43]
	v_readlane_b32 s65, v255, 29
	v_readlane_b32 s68, v255, 32
	v_readlane_b32 s69, v255, 33
	v_readlane_b32 s70, v255, 34
	v_readlane_b32 s71, v255, 35
	s_waitcnt vmcnt(8) lgkmcnt(0)
	v_pk_mul_f32 v[14:15], v[18:19], v[14:15]
	s_waitcnt vmcnt(7)
	v_pk_fma_f32 v[10:11], v[10:11], s[34:35], v[14:15] op_sel_hi:[1,0,1]
	v_pk_mul_f32 v[14:15], v[20:21], v[16:17]
	s_nop 0
	v_pk_fma_f32 v[12:13], v[12:13], s[34:35], v[14:15] op_sel_hi:[1,0,1]
	global_store_dwordx4 v[152:153], v[10:13], off
	ds_read_b128 v[10:13], v158
	s_waitcnt lgkmcnt(0)
	v_pk_mul_f32 v[10:11], v[18:19], v[10:11]
	v_pk_mul_f32 v[12:13], v[20:21], v[12:13]
	s_waitcnt vmcnt(7)
	v_pk_fma_f32 v[10:11], v[102:103], s[34:35], v[10:11] op_sel_hi:[1,0,1]
	v_pk_fma_f32 v[12:13], v[104:105], s[34:35], v[12:13] op_sel_hi:[1,0,1]
	global_store_dwordx4 v[156:157], v[10:13], off
	ds_read_b128 v[10:13], v158 offset:1088
	s_waitcnt lgkmcnt(0)
	v_pk_mul_f32 v[10:11], v[18:19], v[10:11]
	v_pk_mul_f32 v[12:13], v[20:21], v[12:13]
	s_waitcnt vmcnt(7)
; template <int EPI>
; DI void gemm_phase(const P& p, int l, const u16* __restrict__ A, const u16* __restrict__ Bt, int mpx, char* lds) {
;     ...
;     for (int mi = 0; mi < 8; ++mi) {
;       float4 xv[4];
; #pragma unroll
;       for (int i = 0; i < 4; ++i) xv[i] = xn[i];
;       if (mi < 7) {
; #pragma unroll
;         for (int i = 0; i < 4; ++i) xn[i] = *(const float4*)(xr + (size_t)((mi + 1) * 16 + rr0 + 4 * i) * 1024 + c4);
;       }
; #pragma unroll
;       for (int ni = 0; ni < 4; ++ni)
; #pragma unroll
;         for (int j = 0; j < 4; ++j) Cw[(g * 4 + j) * 68 + ni * 16 + r] = acc[mi][ni][j];
;       __builtin_amdgcn_fence(__ATOMIC_RELEASE, "wavefront");
; #pragma unroll
;       for (int i = 0; i < 4; ++i) {
;         const int row = rr0 + 4 * i;
;         const float4 a = *(const float4*)&Cw[row * 68 + c4];
;         float4 z;
;         z.x = alpha * xv[i].x + gt.x * a.x;
;         z.y = alpha * xv[i].y + gt.y * a.y;
;         z.z = alpha * xv[i].z + gt.z * a.z;
;         z.w = alpha * xv[i].w + gt.w * a.w;
;         *(float4*)(Z + (size_t)(mi * 16 + row) * 1024 + c4) = z;
;       }
	v_pk_fma_f32 v[10:11], v[94:95], s[34:35], v[10:11] op_sel_hi:[1,0,1]
	v_pk_fma_f32 v[12:13], v[96:97], s[34:35], v[12:13] op_sel_hi:[1,0,1]
	global_store_dwordx4 v[154:155], v[10:13], off
	ds_read_b128 v[10:13], v158 offset:2176
	s_waitcnt lgkmcnt(0)
	v_pk_mul_f32 v[10:11], v[18:19], v[10:11]
	v_pk_mul_f32 v[12:13], v[20:21], v[12:13]
	s_waitcnt vmcnt(7)
	v_pk_fma_f32 v[10:11], v[86:87], s[34:35], v[10:11] op_sel_hi:[1,0,1]
	v_pk_fma_f32 v[12:13], v[88:89], s[34:35], v[12:13] op_sel_hi:[1,0,1]
	global_store_dwordx4 v[150:151], v[10:13], off
	ds_write2_b32 v165, v138, v142 offset1:16
	ds_write2_b32 v165, v139, v143 offset0:68 offset1:84
	ds_write2_b32 v165, v140, v144 offset0:136 offset1:152
	ds_write2_b32 v165, v141, v145 offset0:204 offset1:220
	ds_write2_b32 v165, v130, v134 offset0:32 offset1:48
	ds_write2_b32 v165, v131, v135 offset0:100 offset1:116
	ds_write2_b32 v165, v132, v136 offset0:168 offset1:184
	ds_write2_b32 v165, v133, v137 offset0:236 offset1:252
	v_add_co_u32_e32 v10, vcc, s33, v162
	s_nop 1
	v_addc_co_u32_e32 v11, vcc, 0, v163, vcc
	global_load_dwordx4 v[110:113], v[10:11], off
	v_add_co_u32_e32 v10, vcc, s2, v162
	s_mov_b32 s2, 0x28000
	s_nop 0
	v_addc_co_u32_e32 v11, vcc, 0, v163, vcc
	global_load_dwordx4 v[102:105], v[10:11], off
	v_add_co_u32_e32 v10, vcc, s2, v162
	s_mov_b32 s2, 0x2c000
	s_nop 0
	v_addc_co_u32_e32 v11, vcc, 0, v163, vcc
	global_load_dwordx4 v[94:97], v[10:11], off
	v_add_co_u32_e32 v10, vcc, s2, v162
	s_mov_b32 s2, 0x34000
	s_nop 0
	v_addc_co_u32_e32 v11, vcc, 0, v163, vcc
	global_load_dwordx4 v[86:89], v[10:11], off
	ds_read_b128 v[10:13], v164
	v_add_co_u32_e32 v14, vcc, s85, v152
	s_waitcnt lgkmcnt(0)
	v_pk_mul_f32 v[10:11], v[18:19], v[10:11]
	v_pk_mul_f32 v[12:13], v[20:21], v[12:13]
	s_waitcnt vmcnt(11)
	v_pk_fma_f32 v[10:11], v[146:147], s[34:35], v[10:11] op_sel_hi:[1,0,1]
	v_pk_fma_f32 v[12:13], v[148:149], s[34:35], v[12:13] op_sel_hi:[1,0,1]
	v_addc_co_u32_e32 v15, vcc, 0, v153, vcc
	global_store_dwordx4 v[14:15], v[10:13], off
	ds_read_b128 v[10:13], v158
	v_add_co_u32_e32 v14, vcc, s85, v156
	s_waitcnt lgkmcnt(0)
	v_pk_mul_f32 v[10:11], v[18:19], v[10:11]
	v_pk_mul_f32 v[12:13], v[20:21], v[12:13]
	s_waitcnt vmcnt(11)
	v_pk_fma_f32 v[10:11], v[106:107], s[34:35], v[10:11] op_sel_hi:[1,0,1]
	v_pk_fma_f32 v[12:13], v[108:109], s[34:35], v[12:13] op_sel_hi:[1,0,1]
	v_addc_co_u32_e32 v15, vcc, 0, v157, vcc
	global_store_dwordx4 v[14:15], v[10:13], off
	ds_read_b128 v[10:13], v158 offset:1088
	v_add_co_u32_e32 v14, vcc, s85, v154
	s_waitcnt lgkmcnt(0)
	v_pk_mul_f32 v[10:11], v[18:19], v[10:11]
	v_pk_mul_f32 v[12:13], v[20:21], v[12:13]
	s_waitcnt vmcnt(11)
	v_pk_fma_f32 v[10:11], v[98:99], s[34:35], v[10:11] op_sel_hi:[1,0,1]
	v_pk_fma_f32 v[12:13], v[100:101], s[34:35], v[12:13] op_sel_hi:[1,0,1]
	v_addc_co_u32_e32 v15, vcc, 0, v155, vcc
	global_store_dwordx4 v[14:15], v[10:13], off
	ds_read_b128 v[10:13], v158 offset:2176
	v_add_co_u32_e32 v14, vcc, s85, v150
	s_waitcnt lgkmcnt(0)
	v_pk_mul_f32 v[10:11], v[18:19], v[10:11]
	v_pk_mul_f32 v[12:13], v[20:21], v[12:13]
	s_waitcnt vmcnt(11)
	v_pk_fma_f32 v[10:11], v[90:91], s[34:35], v[10:11] op_sel_hi:[1,0,1]
	v_pk_fma_f32 v[12:13], v[92:93], s[34:35], v[12:13] op_sel_hi:[1,0,1]
	v_addc_co_u32_e32 v15, vcc, 0, v151, vcc
	global_store_dwordx4 v[14:15], v[10:13], off
	ds_write2_b32 v165, v122, v126 offset1:16
	ds_write2_b32 v165, v123, v127 offset0:68 offset1:84
	ds_write2_b32 v165, v124, v128 offset0:136 offset1:152
	ds_write2_b32 v165, v125, v129 offset0:204 offset1:220
	ds_write2_b32 v165, v114, v118 offset0:32 offset1:48
	ds_write2_b32 v165, v115, v119 offset0:100 offset1:116
	ds_write2_b32 v165, v116, v120 offset0:168 offset1:184
	ds_write2_b32 v165, v117, v121 offset0:236 offset1:252
	v_add_co_u32_e32 v10, vcc, s46, v162
	s_nop 1
	v_addc_co_u32_e32 v11, vcc, 0, v163, vcc
	global_load_dwordx4 v[114:117], v[10:11], off
	v_add_co_u32_e32 v10, vcc, s2, v162
	s_mov_b32 s2, 0x38000
	s_nop 0
	v_addc_co_u32_e32 v11, vcc, 0, v163, vcc
	global_load_dwordx4 v[106:109], v[10:11], off
	v_add_co_u32_e32 v10, vcc, s2, v162
	s_mov_b32 s2, 0x3c000
	s_nop 0
	v_addc_co_u32_e32 v11, vcc, 0, v163, vcc
	global_load_dwordx4 v[98:101], v[10:11], off
	v_add_co_u32_e32 v10, vcc, s2, v162
	s_mov_b32 s2, 0x44000
	s_nop 0
	v_addc_co_u32_e32 v11, vcc, 0, v163, vcc
	global_load_dwordx4 v[90:93], v[10:11], off
	ds_read_b128 v[10:13], v164
	v_add_co_u32_e32 v14, vcc, s33, v152
	s_waitcnt lgkmcnt(0)
	v_pk_mul_f32 v[10:11], v[18:19], v[10:11]
	v_pk_mul_f32 v[12:13], v[20:21], v[12:13]
	s_waitcnt vmcnt(11)
	v_pk_fma_f32 v[10:11], v[110:111], s[34:35], v[10:11] op_sel_hi:[1,0,1]
	v_pk_fma_f32 v[12:13], v[112:113], s[34:35], v[12:13] op_sel_hi:[1,0,1]
	v_addc_co_u32_e32 v15, vcc, 0, v153, vcc
	global_store_dwordx4 v[14:15], v[10:13], off
	ds_read_b128 v[10:13], v158
	v_add_co_u32_e32 v14, vcc, s33, v156
	s_waitcnt lgkmcnt(0)
	v_pk_mul_f32 v[10:11], v[18:19], v[10:11]
	v_pk_mul_f32 v[12:13], v[20:21], v[12:13]
	s_waitcnt vmcnt(11)
	v_pk_fma_f32 v[10:11], v[102:103], s[34:35], v[10:11] op_sel_hi:[1,0,1]
	v_pk_fma_f32 v[12:13], v[104:105], s[34:35], v[12:13] op_sel_hi:[1,0,1]
	v_addc_co_u32_e32 v15, vcc, 0, v157, vcc
	global_store_dwordx4 v[14:15], v[10:13], off
	ds_read_b128 v[10:13], v158 offset:1088
	v_add_co_u32_e32 v14, vcc, s33, v154
	s_waitcnt lgkmcnt(0)
	v_pk_mul_f32 v[10:11], v[18:19], v[10:11]
	v_pk_mul_f32 v[12:13], v[20:21], v[12:13]
	s_waitcnt vmcnt(11)
	v_pk_fma_f32 v[10:11], v[94:95], s[34:35], v[10:11] op_sel_hi:[1,0,1]
	v_pk_fma_f32 v[12:13], v[96:97], s[34:35], v[12:13] op_sel_hi:[1,0,1]
	v_addc_co_u32_e32 v15, vcc, 0, v155, vcc
	global_store_dwordx4 v[14:15], v[10:13], off
	ds_read_b128 v[10:13], v158 offset:2176
	v_add_co_u32_e32 v14, vcc, s33, v150
	s_waitcnt lgkmcnt(0)
; template <int EPI>
; DI void gemm_phase(const P& p, int l, const u16* __restrict__ A, const u16* __restrict__ Bt, int mpx, char* lds) {
;     ...
;     for (int mi = 0; mi < 8; ++mi) {
;       float4 xv[4];
; #pragma unroll
;       for (int i = 0; i < 4; ++i) xv[i] = xn[i];
;       if (mi < 7) {
; #pragma unroll
;         for (int i = 0; i < 4; ++i) xn[i] = *(const float4*)(xr + (size_t)((mi + 1) * 16 + rr0 + 4 * i) * 1024 + c4);
;       }
; #pragma unroll
;       for (int ni = 0; ni < 4; ++ni)
; #pragma unroll
;         for (int j = 0; j < 4; ++j) Cw[(g * 4 + j) * 68 + ni * 16 + r] = acc[mi][ni][j];
;       __builtin_amdgcn_fence(__ATOMIC_RELEASE, "wavefront");
; #pragma unroll
;       for (int i = 0; i < 4; ++i) {
;         const int row = rr0 + 4 * i;
;         const float4 a = *(const float4*)&Cw[row * 68 + c4];
;         float4 z;
;         z.x = alpha * xv[i].x + gt.x * a.x;
;         z.y = alpha * xv[i].y + gt.y * a.y;
;         z.z = alpha * xv[i].z + gt.z * a.z;
;         z.w = alpha * xv[i].w + gt.w * a.w;
;         *(float4*)(Z + (size_t)(mi * 16 + row) * 1024 + c4) = z;
;       }
	v_pk_mul_f32 v[10:11], v[18:19], v[10:11]
	v_pk_mul_f32 v[12:13], v[20:21], v[12:13]
	s_waitcnt vmcnt(11)
	v_pk_fma_f32 v[10:11], v[86:87], s[34:35], v[10:11] op_sel_hi:[1,0,1]
	v_pk_fma_f32 v[12:13], v[88:89], s[34:35], v[12:13] op_sel_hi:[1,0,1]
	v_addc_co_u32_e32 v15, vcc, 0, v151, vcc
	global_store_dwordx4 v[14:15], v[10:13], off
	ds_write2_b32 v165, v78, v82 offset1:16
	ds_write2_b32 v165, v79, v83 offset0:68 offset1:84
	ds_write2_b32 v165, v80, v84 offset0:136 offset1:152
	ds_write2_b32 v165, v81, v85 offset0:204 offset1:220
	ds_write2_b32 v165, v70, v74 offset0:32 offset1:48
	ds_write2_b32 v165, v71, v75 offset0:100 offset1:116
	ds_write2_b32 v165, v72, v76 offset0:168 offset1:184
	ds_write2_b32 v165, v73, v77 offset0:236 offset1:252
	v_add_co_u32_e32 v10, vcc, s35, v162
	s_nop 1
	v_addc_co_u32_e32 v11, vcc, 0, v163, vcc
	global_load_dwordx4 v[82:85], v[10:11], off
	v_add_co_u32_e32 v10, vcc, s2, v162
	s_mov_b32 s2, 0x48000
	s_nop 0
	v_addc_co_u32_e32 v11, vcc, 0, v163, vcc
	global_load_dwordx4 v[78:81], v[10:11], off
	v_add_co_u32_e32 v10, vcc, s2, v162
	s_mov_b32 s2, 0x4c000
	s_nop 0
	v_addc_co_u32_e32 v11, vcc, 0, v163, vcc
	global_load_dwordx4 v[74:77], v[10:11], off
	v_add_co_u32_e32 v10, vcc, s2, v162
	s_mov_b32 s2, 0x54000
	s_nop 0
	v_addc_co_u32_e32 v11, vcc, 0, v163, vcc
	global_load_dwordx4 v[70:73], v[10:11], off
	ds_read_b128 v[10:13], v164
	v_add_co_u32_e32 v14, vcc, s46, v152
	s_waitcnt lgkmcnt(0)
	v_pk_mul_f32 v[10:11], v[18:19], v[10:11]
	v_pk_mul_f32 v[12:13], v[20:21], v[12:13]
	s_waitcnt vmcnt(11)
	v_pk_fma_f32 v[10:11], v[114:115], s[34:35], v[10:11] op_sel_hi:[1,0,1]
	v_pk_fma_f32 v[12:13], v[116:117], s[34:35], v[12:13] op_sel_hi:[1,0,1]
	v_addc_co_u32_e32 v15, vcc, 0, v153, vcc
	global_store_dwordx4 v[14:15], v[10:13], off
	ds_read_b128 v[10:13], v158
	v_add_co_u32_e32 v14, vcc, s46, v156
	s_waitcnt lgkmcnt(0)
	v_pk_mul_f32 v[10:11], v[18:19], v[10:11]
	v_pk_mul_f32 v[12:13], v[20:21], v[12:13]
	s_waitcnt vmcnt(11)
	v_pk_fma_f32 v[10:11], v[106:107], s[34:35], v[10:11] op_sel_hi:[1,0,1]
	v_pk_fma_f32 v[12:13], v[108:109], s[34:35], v[12:13] op_sel_hi:[1,0,1]
	v_addc_co_u32_e32 v15, vcc, 0, v157, vcc
	global_store_dwordx4 v[14:15], v[10:13], off
	ds_read_b128 v[10:13], v158 offset:1088
	v_add_co_u32_e32 v14, vcc, s46, v154
	s_waitcnt lgkmcnt(0)
	v_pk_mul_f32 v[10:11], v[18:19], v[10:11]
	v_pk_mul_f32 v[12:13], v[20:21], v[12:13]
	s_waitcnt vmcnt(11)
	v_pk_fma_f32 v[10:11], v[98:99], s[34:35], v[10:11] op_sel_hi:[1,0,1]
	v_pk_fma_f32 v[12:13], v[100:101], s[34:35], v[12:13] op_sel_hi:[1,0,1]
	v_addc_co_u32_e32 v15, vcc, 0, v155, vcc
	global_store_dwordx4 v[14:15], v[10:13], off
	ds_read_b128 v[10:13], v158 offset:2176
	v_add_co_u32_e32 v14, vcc, s46, v150
	s_mov_b32 s46, 0x50000
	s_nop 0
	v_addc_co_u32_e32 v15, vcc, 0, v151, vcc
	s_waitcnt lgkmcnt(0)
	v_pk_mul_f32 v[10:11], v[18:19], v[10:11]
	v_pk_mul_f32 v[12:13], v[20:21], v[12:13]
	s_waitcnt vmcnt(11)
	v_pk_fma_f32 v[10:11], v[90:91], s[34:35], v[10:11] op_sel_hi:[1,0,1]
	v_pk_fma_f32 v[12:13], v[92:93], s[34:35], v[12:13] op_sel_hi:[1,0,1]
	global_store_dwordx4 v[14:15], v[10:13], off
	ds_write2_b32 v165, v62, v66 offset1:16
	ds_write2_b32 v165, v63, v67 offset0:68 offset1:84
	ds_write2_b32 v165, v64, v68 offset0:136 offset1:152
	ds_write2_b32 v165, v65, v69 offset0:204 offset1:220
	ds_write2_b32 v165, v54, v58 offset0:32 offset1:48
	ds_write2_b32 v165, v55, v59 offset0:100 offset1:116
	ds_write2_b32 v165, v56, v60 offset0:168 offset1:184
	ds_write2_b32 v165, v57, v61 offset0:236 offset1:252
	v_add_co_u32_e32 v10, vcc, s46, v162
	s_nop 1
	v_addc_co_u32_e32 v11, vcc, 0, v163, vcc
	global_load_dwordx4 v[66:69], v[10:11], off
	v_add_co_u32_e32 v10, vcc, s2, v162
	s_mov_b32 s2, 0x58000
	s_nop 0
	v_addc_co_u32_e32 v11, vcc, 0, v163, vcc
	global_load_dwordx4 v[62:65], v[10:11], off
	v_add_co_u32_e32 v10, vcc, s2, v162
	s_mov_b32 s2, 0x5c000
	s_nop 0
	v_addc_co_u32_e32 v11, vcc, 0, v163, vcc
	global_load_dwordx4 v[58:61], v[10:11], off
	v_add_co_u32_e32 v10, vcc, s2, v162
	s_mov_b32 s2, 0x64000
	s_nop 0
	v_addc_co_u32_e32 v11, vcc, 0, v163, vcc
	global_load_dwordx4 v[54:57], v[10:11], off
	ds_read_b128 v[10:13], v164
	v_add_co_u32_e32 v14, vcc, s35, v152
	s_waitcnt lgkmcnt(0)
	v_pk_mul_f32 v[10:11], v[18:19], v[10:11]
	v_pk_mul_f32 v[12:13], v[20:21], v[12:13]
	s_waitcnt vmcnt(11)
	v_pk_fma_f32 v[10:11], v[82:83], s[34:35], v[10:11] op_sel_hi:[1,0,1]
	v_pk_fma_f32 v[12:13], v[84:85], s[34:35], v[12:13] op_sel_hi:[1,0,1]
	v_addc_co_u32_e32 v15, vcc, 0, v153, vcc
	global_store_dwordx4 v[14:15], v[10:13], off
	ds_read_b128 v[10:13], v158
	v_add_co_u32_e32 v14, vcc, s35, v156
	s_waitcnt lgkmcnt(0)
	v_pk_mul_f32 v[10:11], v[18:19], v[10:11]
	v_pk_mul_f32 v[12:13], v[20:21], v[12:13]
	s_waitcnt vmcnt(11)
	v_pk_fma_f32 v[10:11], v[78:79], s[34:35], v[10:11] op_sel_hi:[1,0,1]
	v_pk_fma_f32 v[12:13], v[80:81], s[34:35], v[12:13] op_sel_hi:[1,0,1]
	v_addc_co_u32_e32 v15, vcc, 0, v157, vcc
	global_store_dwordx4 v[14:15], v[10:13], off
	ds_read_b128 v[10:13], v158 offset:1088
	v_add_co_u32_e32 v14, vcc, s35, v154
	s_waitcnt lgkmcnt(0)
	v_pk_mul_f32 v[10:11], v[18:19], v[10:11]
	v_pk_mul_f32 v[12:13], v[20:21], v[12:13]
	s_waitcnt vmcnt(11)
	v_pk_fma_f32 v[10:11], v[74:75], s[34:35], v[10:11] op_sel_hi:[1,0,1]
	v_pk_fma_f32 v[12:13], v[76:77], s[34:35], v[12:13] op_sel_hi:[1,0,1]
	v_addc_co_u32_e32 v15, vcc, 0, v155, vcc
	global_store_dwordx4 v[14:15], v[10:13], off
	ds_read_b128 v[10:13], v158 offset:2176
	v_add_co_u32_e32 v14, vcc, s35, v150
	s_waitcnt lgkmcnt(0)
	v_pk_mul_f32 v[10:11], v[18:19], v[10:11]
	v_pk_mul_f32 v[12:13], v[20:21], v[12:13]
	s_waitcnt vmcnt(11)
; template <int EPI>
; DI void gemm_phase(const P& p, int l, const u16* __restrict__ A, const u16* __restrict__ Bt, int mpx, char* lds) {
;     ...
;     for (int mi = 0; mi < 8; ++mi) {
;       float4 xv[4];
; #pragma unroll
;       for (int i = 0; i < 4; ++i) xv[i] = xn[i];
;       if (mi < 7) {
; #pragma unroll
;         for (int i = 0; i < 4; ++i) xn[i] = *(const float4*)(xr + (size_t)((mi + 1) * 16 + rr0 + 4 * i) * 1024 + c4);
;       }
; #pragma unroll
;       for (int ni = 0; ni < 4; ++ni)
; #pragma unroll
;         for (int j = 0; j < 4; ++j) Cw[(g * 4 + j) * 68 + ni * 16 + r] = acc[mi][ni][j];
;       __builtin_amdgcn_fence(__ATOMIC_RELEASE, "wavefront");
; #pragma unroll
;       for (int i = 0; i < 4; ++i) {
;         const int row = rr0 + 4 * i;
;         const float4 a = *(const float4*)&Cw[row * 68 + c4];
;         float4 z;
;         z.x = alpha * xv[i].x + gt.x * a.x;
;         z.y = alpha * xv[i].y + gt.y * a.y;
;         z.z = alpha * xv[i].z + gt.z * a.z;
;         z.w = alpha * xv[i].w + gt.w * a.w;
;         *(float4*)(Z + (size_t)(mi * 16 + row) * 1024 + c4) = z;
;       }
	v_pk_fma_f32 v[10:11], v[70:71], s[34:35], v[10:11] op_sel_hi:[1,0,1]
	v_pk_fma_f32 v[12:13], v[72:73], s[34:35], v[12:13] op_sel_hi:[1,0,1]
	v_addc_co_u32_e32 v15, vcc, 0, v151, vcc
	global_store_dwordx4 v[14:15], v[10:13], off
	ds_write2_b32 v165, v46, v50 offset1:16
	ds_write2_b32 v165, v47, v51 offset0:68 offset1:84
	ds_write2_b32 v165, v48, v52 offset0:136 offset1:152
	ds_write2_b32 v165, v49, v53 offset0:204 offset1:220
	ds_write2_b32 v165, v38, v42 offset0:32 offset1:48
	ds_write2_b32 v165, v39, v43 offset0:100 offset1:116
	ds_write2_b32 v165, v40, v44 offset0:168 offset1:184
	ds_write2_b32 v165, v41, v45 offset0:236 offset1:252
	v_add_co_u32_e32 v10, vcc, s39, v162
	s_nop 1
	v_addc_co_u32_e32 v11, vcc, 0, v163, vcc
	global_load_dwordx4 v[50:53], v[10:11], off
	v_add_co_u32_e32 v10, vcc, s2, v162
	s_mov_b32 s2, 0x68000
	s_nop 0
	v_addc_co_u32_e32 v11, vcc, 0, v163, vcc
	global_load_dwordx4 v[46:49], v[10:11], off
	v_add_co_u32_e32 v10, vcc, s2, v162
	s_mov_b32 s2, 0x6c000
	s_nop 0
	v_addc_co_u32_e32 v11, vcc, 0, v163, vcc
	global_load_dwordx4 v[42:45], v[10:11], off
	v_add_co_u32_e32 v10, vcc, s2, v162
	s_mov_b32 s2, 0x74000
	s_nop 0
	v_addc_co_u32_e32 v11, vcc, 0, v163, vcc
	global_load_dwordx4 v[38:41], v[10:11], off
	ds_read_b128 v[10:13], v164
	v_add_co_u32_e32 v14, vcc, s46, v152
	s_waitcnt lgkmcnt(0)
	v_pk_mul_f32 v[10:11], v[18:19], v[10:11]
	v_pk_mul_f32 v[12:13], v[20:21], v[12:13]
	s_waitcnt vmcnt(11)
	v_pk_fma_f32 v[10:11], v[66:67], s[34:35], v[10:11] op_sel_hi:[1,0,1]
	v_pk_fma_f32 v[12:13], v[68:69], s[34:35], v[12:13] op_sel_hi:[1,0,1]
	v_addc_co_u32_e32 v15, vcc, 0, v153, vcc
	global_store_dwordx4 v[14:15], v[10:13], off
	ds_read_b128 v[10:13], v158
	v_add_co_u32_e32 v14, vcc, s46, v156
	s_waitcnt lgkmcnt(0)
	v_pk_mul_f32 v[10:11], v[18:19], v[10:11]
	v_pk_mul_f32 v[12:13], v[20:21], v[12:13]
	s_waitcnt vmcnt(11)
	v_pk_fma_f32 v[10:11], v[62:63], s[34:35], v[10:11] op_sel_hi:[1,0,1]
	v_pk_fma_f32 v[12:13], v[64:65], s[34:35], v[12:13] op_sel_hi:[1,0,1]
	v_addc_co_u32_e32 v15, vcc, 0, v157, vcc
	global_store_dwordx4 v[14:15], v[10:13], off
	ds_read_b128 v[10:13], v158 offset:1088
	v_add_co_u32_e32 v14, vcc, s46, v154
	s_waitcnt lgkmcnt(0)
	v_pk_mul_f32 v[10:11], v[18:19], v[10:11]
	v_pk_mul_f32 v[12:13], v[20:21], v[12:13]
	s_waitcnt vmcnt(11)
	v_pk_fma_f32 v[10:11], v[58:59], s[34:35], v[10:11] op_sel_hi:[1,0,1]
	v_pk_fma_f32 v[12:13], v[60:61], s[34:35], v[12:13] op_sel_hi:[1,0,1]
	v_addc_co_u32_e32 v15, vcc, 0, v155, vcc
	global_store_dwordx4 v[14:15], v[10:13], off
	ds_read_b128 v[10:13], v158 offset:2176
	v_add_co_u32_e32 v14, vcc, s46, v150
	s_mov_b32 s46, 0x70000
	s_nop 0
	v_addc_co_u32_e32 v15, vcc, 0, v151, vcc
	s_waitcnt lgkmcnt(0)
	v_pk_mul_f32 v[10:11], v[18:19], v[10:11]
	v_pk_mul_f32 v[12:13], v[20:21], v[12:13]
	s_waitcnt vmcnt(11)
	v_pk_fma_f32 v[10:11], v[54:55], s[34:35], v[10:11] op_sel_hi:[1,0,1]
	v_pk_fma_f32 v[12:13], v[56:57], s[34:35], v[12:13] op_sel_hi:[1,0,1]
	global_store_dwordx4 v[14:15], v[10:13], off
	ds_write2_b32 v165, v30, v34 offset1:16
	ds_write2_b32 v165, v31, v35 offset0:68 offset1:84
	ds_write2_b32 v165, v32, v36 offset0:136 offset1:152
	ds_write2_b32 v165, v33, v37 offset0:204 offset1:220
	ds_write2_b32 v165, v22, v26 offset0:32 offset1:48
	ds_write2_b32 v165, v23, v27 offset0:100 offset1:116
	ds_write2_b32 v165, v24, v28 offset0:168 offset1:184
	ds_write2_b32 v165, v25, v29 offset0:236 offset1:252
	v_add_co_u32_e32 v10, vcc, s46, v162
	s_nop 1
	v_addc_co_u32_e32 v11, vcc, 0, v163, vcc
	global_load_dwordx4 v[10:13], v[10:11], off
	v_add_co_u32_e32 v14, vcc, s2, v162
	s_mov_b32 s2, 0x78000
	s_nop 0
	v_addc_co_u32_e32 v15, vcc, 0, v163, vcc
	global_load_dwordx4 v[30:33], v[14:15], off
	v_add_co_u32_e32 v14, vcc, s2, v162
	s_mov_b32 s2, 0x7c000
	s_nop 0
	v_addc_co_u32_e32 v15, vcc, 0, v163, vcc
	global_load_dwordx4 v[26:29], v[14:15], off
	v_add_co_u32_e32 v14, vcc, s2, v162
	s_nop 1
	v_addc_co_u32_e32 v15, vcc, 0, v163, vcc
	global_load_dwordx4 v[22:25], v[14:15], off
	ds_read_b128 v[14:17], v164
	v_add_co_u32_e32 v34, vcc, s39, v152
	s_waitcnt lgkmcnt(0)
; template <int EPI>
; DI void gemm_phase(const P& p, int l, const u16* __restrict__ A, const u16* __restrict__ Bt, int mpx, char* lds) {
;     ...
;     for (int mi = 0; mi < 8; ++mi) {
;       float4 xv[4];
; #pragma unroll
;       for (int i = 0; i < 4; ++i) xv[i] = xn[i];
;       if (mi < 7) {
; #pragma unroll
;         for (int i = 0; i < 4; ++i) xn[i] = *(const float4*)(xr + (size_t)((mi + 1) * 16 + rr0 + 4 * i) * 1024 + c4);
;       }
; #pragma unroll
;       for (int ni = 0; ni < 4; ++ni)
; #pragma unroll
;         for (int j = 0; j < 4; ++j) Cw[(g * 4 + j) * 68 + ni * 16 + r] = acc[mi][ni][j];
;       __builtin_amdgcn_fence(__ATOMIC_RELEASE, "wavefront");
; #pragma unroll
;       for (int i = 0; i < 4; ++i) {
;         const int row = rr0 + 4 * i;
;         const float4 a = *(const float4*)&Cw[row * 68 + c4];
;         float4 z;
;         z.x = alpha * xv[i].x + gt.x * a.x;
;         z.y = alpha * xv[i].y + gt.y * a.y;
;         z.z = alpha * xv[i].z + gt.z * a.z;
;         z.w = alpha * xv[i].w + gt.w * a.w;
;         *(float4*)(Z + (size_t)(mi * 16 + row) * 1024 + c4) = z;
;       }
;       __builtin_amdgcn_fence(__ATOMIC_RELEASE, "wavefront");
;     }
	v_pk_mul_f32 v[14:15], v[18:19], v[14:15]
	v_pk_mul_f32 v[16:17], v[20:21], v[16:17]
	s_waitcnt vmcnt(11)
	v_pk_fma_f32 v[14:15], v[50:51], s[34:35], v[14:15] op_sel_hi:[1,0,1]
	v_pk_fma_f32 v[16:17], v[52:53], s[34:35], v[16:17] op_sel_hi:[1,0,1]
	v_addc_co_u32_e32 v35, vcc, 0, v153, vcc
	global_store_dwordx4 v[34:35], v[14:17], off
	ds_read_b128 v[14:17], v158
	v_add_co_u32_e32 v34, vcc, s39, v156
	s_waitcnt lgkmcnt(0)
	v_pk_mul_f32 v[14:15], v[18:19], v[14:15]
	v_pk_mul_f32 v[16:17], v[20:21], v[16:17]
	s_waitcnt vmcnt(11)
	v_pk_fma_f32 v[14:15], v[46:47], s[34:35], v[14:15] op_sel_hi:[1,0,1]
	v_pk_fma_f32 v[16:17], v[48:49], s[34:35], v[16:17] op_sel_hi:[1,0,1]
	v_addc_co_u32_e32 v35, vcc, 0, v157, vcc
	global_store_dwordx4 v[34:35], v[14:17], off
	ds_read_b128 v[14:17], v158 offset:1088
	v_add_co_u32_e32 v34, vcc, s39, v154
	s_waitcnt lgkmcnt(0)
	v_pk_mul_f32 v[14:15], v[18:19], v[14:15]
	v_pk_mul_f32 v[16:17], v[20:21], v[16:17]
	s_waitcnt vmcnt(11)
	v_pk_fma_f32 v[14:15], v[42:43], s[34:35], v[14:15] op_sel_hi:[1,0,1]
	v_pk_fma_f32 v[16:17], v[44:45], s[34:35], v[16:17] op_sel_hi:[1,0,1]
	v_addc_co_u32_e32 v35, vcc, 0, v155, vcc
	global_store_dwordx4 v[34:35], v[14:17], off
	ds_read_b128 v[14:17], v158 offset:2176
	v_add_co_u32_e32 v34, vcc, s39, v150
	s_waitcnt lgkmcnt(0)
	v_pk_mul_f32 v[14:15], v[18:19], v[14:15]
	v_pk_mul_f32 v[16:17], v[20:21], v[16:17]
	s_waitcnt vmcnt(11)
	v_pk_fma_f32 v[14:15], v[38:39], s[34:35], v[14:15] op_sel_hi:[1,0,1]
	v_pk_fma_f32 v[16:17], v[40:41], s[34:35], v[16:17] op_sel_hi:[1,0,1]
	v_addc_co_u32_e32 v35, vcc, 0, v151, vcc
	global_store_dwordx4 v[34:35], v[14:17], off
	ds_write2_b32 v165, v166, v170 offset1:16
	ds_write2_b32 v165, v167, v171 offset0:68 offset1:84
	ds_write2_b32 v165, v168, v172 offset0:136 offset1:152
	ds_write2_b32 v165, v169, v173 offset0:204 offset1:220
	ds_write2_b32 v165, v2, v6 offset0:32 offset1:48
	ds_write2_b32 v165, v3, v7 offset0:100 offset1:116
	ds_write2_b32 v165, v4, v8 offset0:168 offset1:184
	ds_write2_b32 v165, v5, v9 offset0:236 offset1:252
	ds_read_b128 v[2:5], v164
	v_add_co_u32_e32 v6, vcc, s46, v152
	s_waitcnt lgkmcnt(0)
	v_pk_mul_f32 v[2:3], v[18:19], v[2:3]
	v_pk_mul_f32 v[4:5], v[20:21], v[4:5]
	v_addc_co_u32_e32 v7, vcc, 0, v153, vcc
	s_waitcnt vmcnt(7)
	v_pk_fma_f32 v[2:3], v[10:11], s[34:35], v[2:3] op_sel_hi:[1,0,1]
	v_pk_fma_f32 v[4:5], v[12:13], s[34:35], v[4:5] op_sel_hi:[1,0,1]
	global_store_dwordx4 v[6:7], v[2:5], off
	ds_read_b128 v[2:5], v158
	v_add_co_u32_e32 v6, vcc, s46, v156
	s_waitcnt lgkmcnt(0)
	v_pk_mul_f32 v[2:3], v[18:19], v[2:3]
	v_pk_mul_f32 v[4:5], v[20:21], v[4:5]
	s_waitcnt vmcnt(7)
	v_pk_fma_f32 v[2:3], v[30:31], s[34:35], v[2:3] op_sel_hi:[1,0,1]
	v_pk_fma_f32 v[4:5], v[32:33], s[34:35], v[4:5] op_sel_hi:[1,0,1]
	v_addc_co_u32_e32 v7, vcc, 0, v157, vcc
	global_store_dwordx4 v[6:7], v[2:5], off
	ds_read_b128 v[2:5], v158 offset:1088
	v_add_co_u32_e32 v6, vcc, s46, v154
	s_mov_b64 s[46:47], s[44:45]
	s_nop 0
	v_addc_co_u32_e32 v7, vcc, 0, v155, vcc
	s_waitcnt lgkmcnt(0)
	v_pk_mul_f32 v[2:3], v[18:19], v[2:3]
	v_pk_mul_f32 v[4:5], v[20:21], v[4:5]
	s_waitcnt vmcnt(7)
	v_pk_fma_f32 v[2:3], v[26:27], s[34:35], v[2:3] op_sel_hi:[1,0,1]
	v_pk_fma_f32 v[4:5], v[28:29], s[34:35], v[4:5] op_sel_hi:[1,0,1]
	global_store_dwordx4 v[6:7], v[2:5], off
	ds_read_b128 v[2:5], v158 offset:2176
	v_add_co_u32_e32 v6, vcc, 0x70000, v150
	s_waitcnt lgkmcnt(0)
	v_pk_mul_f32 v[2:3], v[18:19], v[2:3]
	v_pk_mul_f32 v[4:5], v[20:21], v[4:5]
	v_addc_co_u32_e32 v7, vcc, 0, v151, vcc
	s_waitcnt vmcnt(7)
	v_pk_fma_f32 v[2:3], v[22:23], s[34:35], v[2:3] op_sel_hi:[1,0,1]
	v_pk_fma_f32 v[4:5], v[24:25], s[34:35], v[4:5] op_sel_hi:[1,0,1]
	s_and_b64 vcc, exec, s[40:41]
	global_store_dwordx4 v[6:7], v[2:5], off
	s_cbranch_vccz .LBB0_69
	v_mov_b32_e32 v236, 0x358637bd

; template <int EPI>
; DI void gemm_phase(const P& p, int l, const u16* __restrict__ A, const u16* __restrict__ Bt, int mpx, char* lds) {
;     ...
;   {
;   const int lane = tid & 63, w = tid >> 6, r = lane & 15, g = lane >> 4, wm = w >> 2, wn = w & 3;
;   __syncthreads();
;   GLOAD(Ag, Bg, 64)
;   __builtin_amdgcn_sched_barrier(0);
;   GCOMPUTE_KS(As0, Bs0, 0)
;   __builtin_amdgcn_sched_barrier(0);
;   GSTORE(As1, Bs1)
;   GLOAD(Ag, Bg, 128)
;   __builtin_amdgcn_sched_barrier(0);
;   GCOMPUTE_KS(As0, Bs0, 1)
.LBB0_81:
	v_lshl_add_u64 v[138:139], s[40:41], 0, v[196:197]
	v_add_co_u32_e32 v140, vcc, s33, v138
	v_lshl_add_u64 v[146:147], s[0:1], 0, v[196:197]
	s_nop 0
	v_addc_co_u32_e32 v141, vcc, 0, v139, vcc
	v_add_co_u32_e32 v142, vcc, s35, v138
	s_waitcnt lgkmcnt(0)
	s_nop 0
	v_addc_co_u32_e32 v143, vcc, 0, v139, vcc
	v_add_co_u32_e32 v144, vcc, s39, v138
	s_barrier
	s_nop 0
	v_addc_co_u32_e32 v145, vcc, 0, v139, vcc
	v_add_co_u32_e32 v150, vcc, s33, v146
	s_nop 1
	v_addc_co_u32_e32 v151, vcc, 0, v147, vcc
	v_add_co_u32_e32 v154, vcc, s35, v146
	global_load_dwordx4 v[2:5], v[138:139], off offset:128
	global_load_dwordx4 v[6:9], v[140:141], off offset:128
	v_addc_co_u32_e32 v155, vcc, 0, v147, vcc
	v_add_co_u32_e32 v158, vcc, s39, v146
	global_load_dwordx4 v[10:13], v[142:143], off offset:128
	global_load_dwordx4 v[14:17], v[144:145], off offset:128
	global_load_dwordx4 v[18:21], v[146:147], off offset:128
	global_load_dwordx4 v[22:25], v[150:151], off offset:128
	v_addc_co_u32_e32 v159, vcc, 0, v147, vcc
	global_load_dwordx4 v[26:29], v[154:155], off offset:128
	global_load_dwordx4 v[30:33], v[158:159], off offset:128
	s_mov_b32 s57, s3
	s_lshl_b64 s[42:43], s[56:57], 11
	s_lshl_b32 s2, s51, 11
	s_add_u32 s58, s16, s42
	s_addc_u32 s59, s17, s43
	ds_read_b128 v[34:37], v205
	ds_read_b128 v[38:41], v204 offset:32768
	ds_read_b128 v[42:45], v204 offset:34816
	ds_read_b128 v[46:49], v205 offset:2048
	ds_read_b128 v[58:61], v204 offset:36864
	ds_read_b128 v[62:65], v204 offset:38912
	ds_read_b128 v[82:85], v205 offset:4096
	ds_read_b128 v[86:89], v205 offset:6144
	ds_read_b128 v[114:117], v205 offset:8192
	ds_read_b128 v[118:121], v205 offset:10240
	s_waitcnt vmcnt(25)
	ds_read_b128 v[130:133], v205 offset:12288
	s_waitcnt vmcnt(24)
	ds_read_b128 v[134:137], v205 offset:14336
	s_waitcnt lgkmcnt(10)
	v_mfma_f32_16x16x32_bf16 v[50:53], v[34:37], v[38:41], 0
	s_add_u32 s60, s24, s2
	s_addc_u32 s61, s25, 0
	s_waitcnt lgkmcnt(9)
	v_mfma_f32_16x16x32_bf16 v[54:57], v[34:37], v[42:45], 0
	s_waitcnt lgkmcnt(7)
	v_mfma_f32_16x16x32_bf16 v[66:69], v[34:37], v[58:61], 0
	s_waitcnt lgkmcnt(6)
	v_mfma_f32_16x16x32_bf16 v[34:37], v[34:37], v[62:65], 0
	v_mfma_f32_16x16x32_bf16 v[70:73], v[46:49], v[38:41], 0
	v_mfma_f32_16x16x32_bf16 v[74:77], v[46:49], v[42:45], 0
	v_mfma_f32_16x16x32_bf16 v[78:81], v[46:49], v[58:61], 0
	v_mfma_f32_16x16x32_bf16 v[46:49], v[46:49], v[62:65], 0
	s_waitcnt lgkmcnt(5)
	v_mfma_f32_16x16x32_bf16 v[90:93], v[82:85], v[38:41], 0
	v_mfma_f32_16x16x32_bf16 v[94:97], v[82:85], v[42:45], 0
	v_mfma_f32_16x16x32_bf16 v[98:101], v[82:85], v[58:61], 0
	v_mfma_f32_16x16x32_bf16 v[82:85], v[82:85], v[62:65], 0
	s_waitcnt lgkmcnt(4)
	v_mfma_f32_16x16x32_bf16 v[102:105], v[86:89], v[38:41], 0
	v_mfma_f32_16x16x32_bf16 v[106:109], v[86:89], v[42:45], 0
	v_mfma_f32_16x16x32_bf16 v[110:113], v[86:89], v[58:61], 0
	v_mfma_f32_16x16x32_bf16 v[86:89], v[86:89], v[62:65], 0
	s_waitcnt lgkmcnt(3)
	v_mfma_f32_16x16x32_bf16 v[122:125], v[114:117], v[38:41], 0
	v_mfma_f32_16x16x32_bf16 v[126:129], v[114:117], v[42:45], 0
	v_mfma_f32_16x16x32_bf16 v[162:165], v[114:117], v[58:61], 0
	v_mfma_f32_16x16x32_bf16 v[114:117], v[114:117], v[62:65], 0
	s_waitcnt lgkmcnt(2)
	v_mfma_f32_16x16x32_bf16 v[166:169], v[118:121], v[38:41], 0
	v_mfma_f32_16x16x32_bf16 v[170:173], v[118:121], v[42:45], 0
	v_mfma_f32_16x16x32_bf16 v[174:177], v[118:121], v[58:61], 0
	v_mfma_f32_16x16x32_bf16 v[118:121], v[118:121], v[62:65], 0
	s_waitcnt lgkmcnt(1)
	v_mfma_f32_16x16x32_bf16 v[178:181], v[130:133], v[38:41], 0
	v_mfma_f32_16x16x32_bf16 v[182:185], v[130:133], v[42:45], 0
	v_mfma_f32_16x16x32_bf16 v[186:189], v[130:133], v[58:61], 0
	v_mfma_f32_16x16x32_bf16 v[190:193], v[130:133], v[62:65], 0
	s_waitcnt lgkmcnt(0)
	v_mfma_f32_16x16x32_bf16 v[234:237], v[134:137], v[38:41], 0
	v_mfma_f32_16x16x32_bf16 v[238:241], v[134:137], v[42:45], 0
	v_mfma_f32_16x16x32_bf16 v[242:245], v[134:137], v[58:61], 0
	v_mfma_f32_16x16x32_bf16 v[246:249], v[134:137], v[62:65], 0
	s_waitcnt vmcnt(7)
	ds_write_b128 v202, v[2:5]
	s_waitcnt vmcnt(6)
	ds_write_b128 v227, v[6:9]
	s_waitcnt vmcnt(5)
	ds_write_b128 v228, v[10:13]
	s_waitcnt vmcnt(4)
	ds_write_b128 v229, v[14:17]
	s_waitcnt vmcnt(3)
	ds_write_b128 v203, v[18:21]
	s_waitcnt vmcnt(2)
	ds_write_b128 v230, v[22:25]
	s_waitcnt vmcnt(1)
	ds_write_b128 v231, v[26:29]
	s_waitcnt vmcnt(0)
; template <int EPI>
; DI void gemm_phase(const P& p, int l, const u16* __restrict__ A, const u16* __restrict__ Bt, int mpx, char* lds) {
;     ...
;   GLOAD(Ag, Bg, 128)
;   __builtin_amdgcn_sched_barrier(0);
;   GCOMPUTE_KS(As0, Bs0, 1)
;   __builtin_amdgcn_sched_barrier(0);
; #pragma unroll 1
;   for (int kk = 1; kk < 15; kk += 2) {
;     __syncthreads();
	ds_write_b128 v232, v[30:33]
	global_load_dwordx4 v[130:133], v[138:139], off offset:256
	global_load_dwordx4 v[134:137], v[140:141], off offset:256
	s_nop 0
	global_load_dwordx4 v[138:141], v[142:143], off offset:256
	s_nop 0
	global_load_dwordx4 v[142:145], v[144:145], off offset:256
	s_nop 0
	global_load_dwordx4 v[146:149], v[146:147], off offset:256
	s_nop 0
	global_load_dwordx4 v[150:153], v[150:151], off offset:256
	s_nop 0
	global_load_dwordx4 v[154:157], v[154:155], off offset:256
	s_nop 0
	global_load_dwordx4 v[158:161], v[158:159], off offset:256
	ds_read_b128 v[2:5], v207
	ds_read_b128 v[250:253], v206 offset:32768
	ds_read_b128 v[216:219], v206 offset:34816
	ds_read_b128 v[212:215], v206 offset:36864
	ds_read_b128 v[220:223], v206 offset:38912
	s_waitcnt lgkmcnt(3)
	v_mfma_f32_16x16x32_bf16 v[6:9], v[2:5], v[250:253], v[50:53]
	s_waitcnt lgkmcnt(2)
	v_mfma_f32_16x16x32_bf16 v[10:13], v[2:5], v[216:219], v[54:57]
	s_waitcnt lgkmcnt(1)
	v_mfma_f32_16x16x32_bf16 v[14:17], v[2:5], v[212:215], v[66:69]
	s_waitcnt lgkmcnt(0)
	v_mfma_f32_16x16x32_bf16 v[18:21], v[2:5], v[220:223], v[34:37]
	ds_read_b128 v[2:5], v207 offset:2048
	s_waitcnt lgkmcnt(0)
	v_mfma_f32_16x16x32_bf16 v[22:25], v[2:5], v[250:253], v[70:73]
	v_mfma_f32_16x16x32_bf16 v[26:29], v[2:5], v[216:219], v[74:77]
	v_mfma_f32_16x16x32_bf16 v[30:33], v[2:5], v[212:215], v[78:81]
	v_mfma_f32_16x16x32_bf16 v[34:37], v[2:5], v[220:223], v[46:49]
	ds_read_b128 v[2:5], v207 offset:4096
	s_waitcnt lgkmcnt(0)
	v_mfma_f32_16x16x32_bf16 v[38:41], v[2:5], v[250:253], v[90:93]
	v_mfma_f32_16x16x32_bf16 v[42:45], v[2:5], v[216:219], v[94:97]
	v_mfma_f32_16x16x32_bf16 v[46:49], v[2:5], v[212:215], v[98:101]
	v_mfma_f32_16x16x32_bf16 v[50:53], v[2:5], v[220:223], v[82:85]
	ds_read_b128 v[2:5], v207 offset:6144
	s_waitcnt lgkmcnt(0)
	v_mfma_f32_16x16x32_bf16 v[54:57], v[2:5], v[250:253], v[102:105]
	v_mfma_f32_16x16x32_bf16 v[58:61], v[2:5], v[216:219], v[106:109]
	v_mfma_f32_16x16x32_bf16 v[62:65], v[2:5], v[212:215], v[110:113]
	v_mfma_f32_16x16x32_bf16 v[66:69], v[2:5], v[220:223], v[86:89]
	ds_read_b128 v[2:5], v207 offset:8192
	s_waitcnt lgkmcnt(0)
	v_mfma_f32_16x16x32_bf16 v[70:73], v[2:5], v[250:253], v[122:125]
	v_mfma_f32_16x16x32_bf16 v[74:77], v[2:5], v[216:219], v[126:129]
	v_mfma_f32_16x16x32_bf16 v[78:81], v[2:5], v[212:215], v[162:165]
	v_mfma_f32_16x16x32_bf16 v[82:85], v[2:5], v[220:223], v[114:117]
	ds_read_b128 v[2:5], v207 offset:10240
	s_waitcnt lgkmcnt(0)
	v_mfma_f32_16x16x32_bf16 v[86:89], v[2:5], v[250:253], v[166:169]
	v_mfma_f32_16x16x32_bf16 v[90:93], v[2:5], v[216:219], v[170:173]
	v_mfma_f32_16x16x32_bf16 v[94:97], v[2:5], v[212:215], v[174:177]
	v_mfma_f32_16x16x32_bf16 v[98:101], v[2:5], v[220:223], v[118:121]
	ds_read_b128 v[2:5], v207 offset:12288
	s_waitcnt lgkmcnt(0)
	v_mfma_f32_16x16x32_bf16 v[102:105], v[2:5], v[250:253], v[178:181]
	v_mfma_f32_16x16x32_bf16 v[106:109], v[2:5], v[216:219], v[182:185]
	v_mfma_f32_16x16x32_bf16 v[110:113], v[2:5], v[212:215], v[186:189]
	v_mfma_f32_16x16x32_bf16 v[114:117], v[2:5], v[220:223], v[190:193]
	ds_read_b128 v[2:5], v207 offset:14336
	s_waitcnt lgkmcnt(0)
	v_mfma_f32_16x16x32_bf16 v[118:121], v[2:5], v[250:253], v[234:237]
	v_mfma_f32_16x16x32_bf16 v[122:125], v[2:5], v[216:219], v[238:241]
	v_mfma_f32_16x16x32_bf16 v[126:129], v[2:5], v[212:215], v[242:245]
	v_mfma_f32_16x16x32_bf16 v[2:5], v[2:5], v[220:223], v[246:249]
	s_mov_b32 s49, 1
	s_movk_i32 s47, 0x100
	s_mov_b64 s[42:43], s[0:1]
	s_mov_b64 s[44:45], s[40:41]
	v_add_u32_e32 v208, s33, v196
	v_add_u32_e32 v209, s35, v196
	v_add_u32_e32 v210, s39, v196
	v_readfirstlane_b32 s98, v195
	s_cmpk_lt_u32 s98, 0x100
	s_cbranch_scc1 .Lprio_skip_1
	s_setprio 1
.Lprio_skip_1:
	s_barrier
	ds_read_b128 v[212:215], v198
	ds_read_b128 v[216:219], v198 offset:2048
	ds_read_b128 v[220:223], v198 offset:4096
	ds_read_b128 v[234:237], v198 offset:6144
	ds_read_b128 v[238:241], v199
	ds_read_b128 v[242:245], v199 offset:2048
	ds_read_b128 v[246:249], v199 offset:4096
	ds_read_b128 v[250:253], v199 offset:6144
	global_load_dwordx4 v[162:165], v196, s[44:45] offset:384
	global_load_dwordx4 v[166:169], v208, s[44:45] offset:384
	global_load_dwordx4 v[170:173], v209, s[44:45] offset:384
	global_load_dwordx4 v[174:177], v210, s[44:45] offset:384
	global_load_dwordx4 v[178:181], v196, s[42:43] offset:384
	global_load_dwordx4 v[182:185], v208, s[42:43] offset:384
	global_load_dwordx4 v[186:189], v209, s[42:43] offset:384
	global_load_dwordx4 v[190:193], v210, s[42:43] offset:384

; #define GCOMPUTE(AS, BS) GCOMPUTE_KS(AS, BS, 0) GCOMPUTE_KS(AS, BS, 1)
; template <int EPI>
; DI void gemm_phase(const P& p, int l, const u16* __restrict__ A, const u16* __restrict__ Bt, int mpx, char* lds) {
;     ...
;     __builtin_amdgcn_sched_barrier(0);
;     GCOMPUTE(As0, Bs0)
;     __builtin_amdgcn_sched_barrier(0);
;   }
;   __syncthreads();
;   __builtin_amdgcn_sched_barrier(0);
;   GCOMPUTE(As1, Bs1)
;   __builtin_amdgcn_sched_barrier(0);
.Lgemm_in_exit:
	s_setprio 0
	v_mfma_f32_16x16x32_bf16 v[102:105], v[246:249], v[162:165], v[102:105]
	v_mfma_f32_16x16x32_bf16 v[106:109], v[246:249], v[166:169], v[106:109]
	v_mfma_f32_16x16x32_bf16 v[110:113], v[246:249], v[170:173], v[110:113]
	v_mfma_f32_16x16x32_bf16 v[114:117], v[246:249], v[174:177], v[114:117]
	v_mfma_f32_16x16x32_bf16 v[118:121], v[250:253], v[162:165], v[118:121]
	v_mfma_f32_16x16x32_bf16 v[122:125], v[250:253], v[166:169], v[122:125]
	v_mfma_f32_16x16x32_bf16 v[126:129], v[250:253], v[170:173], v[126:129]
	v_mfma_f32_16x16x32_bf16 v[2:5], v[250:253], v[174:177], v[2:5]
	s_barrier
	ds_read_b128 v[162:165], v199
	ds_read_b128 v[166:169], v198
	ds_read_b128 v[170:173], v198 offset:2048
	ds_read_b128 v[174:177], v198 offset:4096
	ds_read_b128 v[178:181], v198 offset:6144
	s_waitcnt lgkmcnt(3)
	v_mfma_f32_16x16x32_bf16 v[6:9], v[162:165], v[166:169], v[6:9]
	s_waitcnt lgkmcnt(2)
	v_mfma_f32_16x16x32_bf16 v[10:13], v[162:165], v[170:173], v[10:13]
	s_waitcnt lgkmcnt(1)
	v_mfma_f32_16x16x32_bf16 v[14:17], v[162:165], v[174:177], v[14:17]
	s_waitcnt lgkmcnt(0)
	v_mfma_f32_16x16x32_bf16 v[18:21], v[162:165], v[178:181], v[18:21]
	ds_read_b128 v[162:165], v199 offset:2048
	s_waitcnt lgkmcnt(0)
	v_mfma_f32_16x16x32_bf16 v[22:25], v[162:165], v[166:169], v[22:25]
	v_mfma_f32_16x16x32_bf16 v[26:29], v[162:165], v[170:173], v[26:29]
	v_mfma_f32_16x16x32_bf16 v[30:33], v[162:165], v[174:177], v[30:33]
	v_mfma_f32_16x16x32_bf16 v[34:37], v[162:165], v[178:181], v[34:37]
	ds_read_b128 v[162:165], v199 offset:4096
	s_waitcnt lgkmcnt(0)
	v_mfma_f32_16x16x32_bf16 v[38:41], v[162:165], v[166:169], v[38:41]
	v_mfma_f32_16x16x32_bf16 v[42:45], v[162:165], v[170:173], v[42:45]
	v_mfma_f32_16x16x32_bf16 v[46:49], v[162:165], v[174:177], v[46:49]
	v_mfma_f32_16x16x32_bf16 v[50:53], v[162:165], v[178:181], v[50:53]
	ds_read_b128 v[162:165], v199 offset:6144
	s_waitcnt lgkmcnt(0)
	v_mfma_f32_16x16x32_bf16 v[54:57], v[162:165], v[166:169], v[54:57]
	v_mfma_f32_16x16x32_bf16 v[58:61], v[162:165], v[170:173], v[58:61]
	v_mfma_f32_16x16x32_bf16 v[62:65], v[162:165], v[174:177], v[62:65]
	v_mfma_f32_16x16x32_bf16 v[66:69], v[162:165], v[178:181], v[66:69]
	ds_read_b128 v[162:165], v199 offset:8192
	s_waitcnt lgkmcnt(0)
	v_mfma_f32_16x16x32_bf16 v[182:185], v[162:165], v[166:169], v[70:73]
	s_nop 2
	ds_read_b128 v[70:73], v199 offset:10240
	v_mfma_f32_16x16x32_bf16 v[186:189], v[162:165], v[170:173], v[74:77]
	s_nop 2
	ds_read_b128 v[74:77], v233
	s_waitcnt lgkmcnt(1)
	v_mfma_f32_16x16x32_bf16 v[212:215], v[70:73], v[166:169], v[86:89]
	v_mfma_f32_16x16x32_bf16 v[216:219], v[70:73], v[170:173], v[90:93]
	v_mfma_f32_16x16x32_bf16 v[220:223], v[70:73], v[174:177], v[94:97]
	v_mfma_f32_16x16x32_bf16 v[234:237], v[70:73], v[178:181], v[98:101]
	ds_read_b128 v[70:73], v199 offset:12288
	s_waitcnt lgkmcnt(0)
	v_mfma_f32_16x16x32_bf16 v[238:241], v[70:73], v[166:169], v[102:105]
	v_mfma_f32_16x16x32_bf16 v[242:245], v[70:73], v[170:173], v[106:109]
	v_mfma_f32_16x16x32_bf16 v[246:249], v[70:73], v[174:177], v[110:113]
	v_mfma_f32_16x16x32_bf16 v[250:253], v[70:73], v[178:181], v[114:117]
	ds_read_b128 v[70:73], v199 offset:14336
	v_mfma_f32_16x16x32_bf16 v[190:193], v[162:165], v[174:177], v[78:81]
	v_mfma_f32_16x16x32_bf16 v[162:165], v[162:165], v[178:181], v[82:85]
	s_waitcnt lgkmcnt(0)
	v_mfma_f32_16x16x32_bf16 v[178:181], v[70:73], v[178:181], v[2:5]
	s_nop 2
	ds_read_b128 v[2:5], v200
	v_mfma_f32_16x16x32_bf16 v[174:177], v[70:73], v[174:177], v[126:129]
	s_waitcnt lgkmcnt(0)
	v_mfma_f32_16x16x32_bf16 v[126:129], v[74:77], v[2:5], v[6:9]
	s_nop 2
	ds_read_b128 v[6:9], v200 offset:2048
	v_mfma_f32_16x16x32_bf16 v[170:173], v[70:73], v[170:173], v[122:125]
	s_waitcnt lgkmcnt(0)
	v_mfma_f32_16x16x32_bf16 v[122:125], v[74:77], v[6:9], v[10:13]
	s_nop 2
	ds_read_b128 v[10:13], v200 offset:4096
	v_mfma_f32_16x16x32_bf16 v[166:169], v[70:73], v[166:169], v[118:121]
	s_waitcnt lgkmcnt(0)
	v_mfma_f32_16x16x32_bf16 v[118:121], v[74:77], v[10:13], v[14:17]
	s_nop 2
	ds_read_b128 v[14:17], v200 offset:6144
	s_waitcnt lgkmcnt(0)
	v_mfma_f32_16x16x32_bf16 v[114:117], v[74:77], v[14:17], v[18:21]
	s_nop 2
	ds_read_b128 v[18:21], v233 offset:2048
	s_waitcnt lgkmcnt(0)
	v_mfma_f32_16x16x32_bf16 v[110:113], v[18:21], v[2:5], v[22:25]
	v_mfma_f32_16x16x32_bf16 v[106:109], v[18:21], v[6:9], v[26:29]
	v_mfma_f32_16x16x32_bf16 v[102:105], v[18:21], v[10:13], v[30:33]
	v_mfma_f32_16x16x32_bf16 v[98:101], v[18:21], v[14:17], v[34:37]
	ds_read_b128 v[18:21], v233 offset:4096
	s_waitcnt lgkmcnt(0)
	v_mfma_f32_16x16x32_bf16 v[94:97], v[18:21], v[2:5], v[38:41]
	v_mfma_f32_16x16x32_bf16 v[90:93], v[18:21], v[6:9], v[42:45]
	v_mfma_f32_16x16x32_bf16 v[86:89], v[18:21], v[10:13], v[46:49]
	v_mfma_f32_16x16x32_bf16 v[82:85], v[18:21], v[14:17], v[50:53]
	ds_read_b128 v[18:21], v233 offset:6144
	s_waitcnt lgkmcnt(0)
	v_mfma_f32_16x16x32_bf16 v[78:81], v[18:21], v[2:5], v[54:57]
	v_mfma_f32_16x16x32_bf16 v[74:77], v[18:21], v[6:9], v[58:61]
	v_mfma_f32_16x16x32_bf16 v[70:73], v[18:21], v[10:13], v[62:65]
	v_mfma_f32_16x16x32_bf16 v[66:69], v[18:21], v[14:17], v[66:69]
	ds_read_b128 v[18:21], v233 offset:8192
	s_waitcnt lgkmcnt(0)
	v_mfma_f32_16x16x32_bf16 v[62:65], v[18:21], v[2:5], v[182:185]
	s_nop 2
	ds_read_b128 v[182:185], v233 offset:14336
	v_mfma_f32_16x16x32_bf16 v[58:61], v[18:21], v[6:9], v[186:189]
	v_mfma_f32_16x16x32_bf16 v[54:57], v[18:21], v[10:13], v[190:193]
	v_mfma_f32_16x16x32_bf16 v[50:53], v[18:21], v[14:17], v[162:165]
	ds_read_b128 v[18:21], v233 offset:10240
	s_waitcnt lgkmcnt(0)
	v_mfma_f32_16x16x32_bf16 v[46:49], v[18:21], v[2:5], v[212:215]
	v_mfma_f32_16x16x32_bf16 v[42:45], v[18:21], v[6:9], v[216:219]
	v_mfma_f32_16x16x32_bf16 v[38:41], v[18:21], v[10:13], v[220:223]
	v_mfma_f32_16x16x32_bf16 v[34:37], v[18:21], v[14:17], v[234:237]
	ds_read_b128 v[18:21], v233 offset:12288
	s_waitcnt lgkmcnt(0)
	v_mfma_f32_16x16x32_bf16 v[30:33], v[18:21], v[2:5], v[238:241]
	v_mfma_f32_16x16x32_bf16 v[26:29], v[18:21], v[6:9], v[242:245]
	v_mfma_f32_16x16x32_bf16 v[22:25], v[18:21], v[10:13], v[246:249]
	v_mfma_f32_16x16x32_bf16 v[18:21], v[18:21], v[14:17], v[250:253]
	v_mfma_f32_16x16x32_bf16 v[166:169], v[182:185], v[2:5], v[166:169]
	v_mfma_f32_16x16x32_bf16 v[162:165], v[182:185], v[6:9], v[170:173]
	v_mfma_f32_16x16x32_bf16 v[2:5], v[182:185], v[10:13], v[174:177]
	v_mfma_f32_16x16x32_bf16 v[6:9], v[182:185], v[14:17], v[178:181]
	s_barrier
; template <int EPI>
; DI void gemm_phase(const P& p, int l, const u16* __restrict__ A, const u16* __restrict__ Bt, int mpx, char* lds) {
;     ...
;   __syncthreads();
;   GSTORE(As0, Bs0)
;     ...
;     const int cb = n0 + wn * 64;
;     const bool isctx = m0 >= MLAT;
;     const int b = isctx ? ((m0 - MLAT) >> 8) : (m0 >> 11);
;     const int tokw = (isctx ? 2048 + ((m0 - MLAT) & 255) : (m0 & 2047)) + wm * 128;
;     u16* Tl = (u16*)(lds + 65536) + w * (64 * 72);
;     int kind = 0;
;     int tr = 0;
;     bool donorm = false;
;     if (cb >= 2816) { kind = 2; tr = 1; }
;     else if (cb < 256) tr = 1;
;     else if (cb < 512) tr = 0;
;     else if (cb < 1024) tr = 2;
;     else if (cb < 1408) { tr = 3; donorm = true; }
;     else if (cb < 1536) kind = 1;
;     else if (cb < 2048) tr = isctx ? 0 : 4;
;     else if (cb < 2304) kind = 1;
;     else if (cb < 2688) tr = isctx ? 0 : 3;
;     else kind = 1;
	s_waitcnt vmcnt(7)
	ds_write_b128 v201, v[130:133]
	s_waitcnt vmcnt(5)
	ds_write_b128 v201, v[134:137] offset:8192
	s_waitcnt vmcnt(4)
	ds_write_b128 v201, v[138:141] offset:16384
	s_waitcnt vmcnt(3)
	ds_write_b128 v201, v[142:145] offset:24576
	ds_write_b128 v201, v[146:149] offset:32768
	s_waitcnt vmcnt(2)
	ds_write_b128 v201, v[150:153] offset:40960
	s_waitcnt vmcnt(1)
	ds_write_b128 v201, v[154:157] offset:49152
	s_waitcnt vmcnt(0)
	ds_write_b128 v201, v[158:161] offset:57344
	v_readfirstlane_b32 s40, v195
	s_lshr_b32 s40, s40, 6
	s_and_b32 s41, s40, 3
	s_lshr_b32 s42, s40, 2
	s_lshr_b32 s43, s46, 6
	s_add_i32 s43, s43, s41
	s_cmp_ge_u32 s66, 0x8000
	s_cselect_b32 s67, 1, 0
	s_mov_b32 s44, 0xffff
	s_mov_b32 s45, 0
	s_bitcmp1_b64 s[44:45], s43
	s_cbranch_scc1 .Lfe_kind0
	s_mov_b32 s44, 0xc00000
	s_mov_b32 s45, 0xc0f
	s_bitcmp1_b64 s[44:45], s43
	s_cbranch_scc1 .Lfe_kind1
	s_cmp_ge_u32 s43, 44
	s_cbranch_scc1 .Lfe_kind2
	s_branch .Lfe_kind0

; __global__ void __launch_bounds__(512, 2) mega(P p) {
;   extern __shared__ __attribute__((aligned(16))) char lds[];
	.amdhsa_kernel _Z4mega1P
		.amdhsa_group_segment_fixed_size 32
		.amdhsa_private_segment_fixed_size 0
		.amdhsa_kernarg_size 488
		.amdhsa_user_sgpr_count 2
		.amdhsa_user_sgpr_dispatch_ptr 0
		.amdhsa_user_sgpr_queue_ptr 0
		.amdhsa_user_sgpr_kernarg_segment_ptr 1
		.amdhsa_user_sgpr_dispatch_id 0
		.amdhsa_user_sgpr_kernarg_preload_length 0
		.amdhsa_user_sgpr_kernarg_preload_offset 0
		.amdhsa_user_sgpr_private_segment_size 0
		.amdhsa_uses_dynamic_stack 0
		.amdhsa_enable_private_segment 0
		.amdhsa_system_sgpr_workgroup_id_x 1
		.amdhsa_system_sgpr_workgroup_id_y 0
		.amdhsa_system_sgpr_workgroup_id_z 0
		.amdhsa_system_sgpr_workgroup_info 0
		.amdhsa_system_vgpr_workitem_id 2
		.amdhsa_next_free_vgpr 256
		.amdhsa_next_free_sgpr 102
		.amdhsa_accum_offset 256
		.amdhsa_reserve_vcc 1
		.amdhsa_float_round_mode_32 0
		.amdhsa_float_round_mode_16_64 0
		.amdhsa_float_denorm_mode_32 3
		.amdhsa_float_denorm_mode_16_64 3
		.amdhsa_dx10_clamp 1
		.amdhsa_ieee_mode 1
		.amdhsa_fp16_overflow 0
		.amdhsa_tg_split 0
		.amdhsa_exception_fp_ieee_invalid_op 0
		.amdhsa_exception_fp_denorm_src 0
		.amdhsa_exception_fp_ieee_div_zero 0
		.amdhsa_exception_fp_ieee_overflow 0
		.amdhsa_exception_fp_ieee_underflow 0
		.amdhsa_exception_fp_ieee_inexact 0
		.amdhsa_exception_int_div_zero 0
	.end_amdhsa_kernel

; __global__ void __launch_bounds__(512, 2) mega(P p) {
;   extern __shared__ __attribute__((aligned(16))) char lds[];
amdhsa.kernels:
  - .agpr_count:     0
    .args:
      - .offset:         0
        .size:           232
        .value_kind:     by_value
      - .offset:         232
        .size:           4
        .value_kind:     hidden_block_count_x
      - .offset:         236
        .size:           4
        .value_kind:     hidden_block_count_y
      - .offset:         240
        .size:           4
        .value_kind:     hidden_block_count_z
      - .offset:         244
        .size:           2
        .value_kind:     hidden_group_size_x
      - .offset:         246
        .size:           2
        .value_kind:     hidden_group_size_y
      - .offset:         248
        .size:           2
        .value_kind:     hidden_group_size_z
      - .offset:         250
        .size:           2
        .value_kind:     hidden_remainder_x
      - .offset:         252
        .size:           2
        .value_kind:     hidden_remainder_y
      - .offset:         254
        .size:           2
        .value_kind:     hidden_remainder_z
      - .offset:         272
        .size:           8
        .value_kind:     hidden_global_offset_x
      - .offset:         280
        .size:           8
        .value_kind:     hidden_global_offset_y
      - .offset:         288
        .size:           8
        .value_kind:     hidden_global_offset_z
      - .offset:         296
        .size:           2
        .value_kind:     hidden_grid_dims
      - .offset:         320
        .size:           8
        .value_kind:     hidden_multigrid_sync_arg
      - .offset:         352
        .size:           4
        .value_kind:     hidden_dynamic_lds_size
    .group_segment_fixed_size: 32
    .kernarg_segment_align: 8
    .kernarg_segment_size: 488
    .language:       OpenCL C
    .language_version:
      - 2
      - 0
    .max_flat_workgroup_size: 512
    .name:           _Z4mega1P
    .private_segment_fixed_size: 0
    .sgpr_count:     108
    .sgpr_spill_count: 124
    .symbol:         _Z4mega1P.kd
    .uniform_work_group_size: 1
    .uses_dynamic_stack: false
    .vgpr_count:     256
    .vgpr_spill_count: 0
    .wavefront_size: 64
